# hand-written P1 epilogues for unit kinds 1 and 2 (packed f32 math, 6 transcendentals per gate triple) on top of conv31 rewrite and fused W_o epilogue
# speedup vs baseline: 1.0475x; 1.0078x over previous
; __device__ __forceinline__ float sigmoidf_(float x) { return __builtin_amdgcn_rcpf(1.0f + __builtin_amdgcn_exp2f(-1.44269504089f * x)); }
; __device__ __forceinline__ u32x2 pk4(f32x4 v) { u32x2 r; r.x = pk_bf16(v[0], v[1]); r.y = pk_bf16(v[2], v[3]); return r; }
; __device__ __forceinline__ int pf(int fq) { return (fq >> 1) | ((fq & 1) << 1); }
;     __device__ __forceinline__ void operator()(const f32x4 (&acc)[2][2][4][2], const Unit& u, int wr, int wc, int fr, int fq) const {
;     ...
;             } else {
; #pragma unroll
;                 for (int ai = 0; ai < 2; ++ai) {
;                     u32x2 qv[4];
; #pragma unroll
;                     for (int m = 0; m < 4; ++m) {
;                         const f32x4 Qv = acc[ai][0][m][0], Ga = acc[ai][0][m][1], Gb = acc[ai][1][m][0], Gx = acc[ai][1][m][1]; f32x4 o1, o2, o3;
; #pragma unroll
;                         for (int j = 0; j < 4; ++j) { const float sa = sigmoidf_(Ga[j]), sb = sigmoidf_(Gb[j]), sx = sigmoidf_(Gx[j]);
;                             o1[j] = sa * __builtin_amdgcn_rcpf(fmaxf(sb, 1e-30f)); o2[j] = sb * __builtin_amdgcn_rcpf(fmaxf(sx, 1e-30f)); o3[j] = sx; }
;                         qv[m] = pk4(Qv * 0.0625f);
;                         const int c = (u.pn & 3) * 64 + wc * 16;
;                         const size_t ns = native_slot(u.pm, (u.pn & 15) >> 2, wr * 4 + ((c >> 5) & 3), ai, m, c >> 7, (c >> 4) & 1, pf(fq) * 16 + fr);
;                         __builtin_nontemporal_store(pk4(o1), (u32x2*)SGA + ns); __builtin_nontemporal_store(pk4(o2), (u32x2*)SGB + ns); __builtin_nontemporal_store(pk4(o3), (u32x2*)SGX + ns);
;                     }
; #pragma unroll
;                     for (int pr = 0; pr < 2; ++pr) store_pair16(Q + (size_t)(rowb + ai * 128 + pr * 32) * 1024 + chw, qv[2 * pr], qv[2 * pr + 1], fq);
;                 }
.LBB0_269:
	s_cmp_eq_u32 s13, 1
	s_cbranch_scc1 .Lp1e_k1
	s_cmp_eq_u32 s13, 2
	s_cbranch_scc0 .Lp1e_k0
	v_mbcnt_lo_u32_b32 v240, -1, 0
	v_mbcnt_hi_u32_b32 v240, -1, v240
	v_readlane_b32 s4, v255, 19
	s_nop 3
	s_lshr_b32 s4, s4, 6
	s_lshr_b32 s5, s4, 2
	s_and_b32 s30, s4, 3
	v_and_b32_e32 v241, 15, v240
	v_lshrrev_b32_e32 v242, 4, v240
	v_lshrrev_b32_e32 v243, 1, v242
	v_and_b32_e32 v244, 1, v242
	v_lshl_or_b32 v248, v244, 1, v243
	v_lshl_add_u32 v248, v248, 4, v241
	v_lshl_add_u32 v246, v243, 4, v241
	v_lshlrev_b32_e32 v243, 3, v248
	s_lshl_b32 s31, s96, 8
	s_lshl_b32 s64, s5, 6
	s_add_i32 s31, s31, s64
	v_add_u32_e32 v246, s31, v246
	v_mov_b32_e32 v247, 0
	v_lshlrev_b64 v[246:247], 11, v[246:247]
	s_and_b32 s64, s90, 15
	s_lshl_b32 s64, s64, 6
	s_lshl_b32 vcc_lo, s30, 4
	s_add_i32 s64, s64, vcc_lo
	v_lshlrev_b32_e32 v244, 3, v244
	v_add_u32_e32 v244, s64, v244
	v_lshlrev_b32_e32 v244, 1, v244
	v_mov_b32_e32 v245, 0
	v_lshl_add_u64 v[246:247], v[246:247], 0, v[244:245]
	s_lshl_b32 s64, s96, 2
	s_bfe_u32 vcc_lo, s90, 0x20002
	s_add_i32 s64, s64, vcc_lo
	s_lshl_b32 s64, s64, 17
	s_lshl_b32 vcc_lo, s5, 2
	s_and_b32 vcc_hi, s90, 1
	s_lshl_b32 vcc_hi, vcc_hi, 1
	s_add_i32 vcc_lo, vcc_lo, vcc_hi
	s_lshr_b32 vcc_hi, s30, 1
	s_add_i32 vcc_lo, vcc_lo, vcc_hi
	s_lshl_b32 vcc_lo, vcc_lo, 14
	s_add_i32 s64, s64, vcc_lo
	s_bfe_u32 vcc_lo, s90, 0x10001
	s_lshl_b32 vcc_lo, vcc_lo, 1
	s_and_b32 vcc_hi, s30, 1
	s_add_i32 vcc_lo, vcc_lo, vcc_hi
	s_lshl_b32 vcc_lo, vcc_lo, 9
	s_add_i32 s64, s64, vcc_lo
	s_mov_b32 s42, 0xbfb8aa3b
	s_mov_b32 s43, 1.0
	s_add_u32 s98, s18, s64
	s_addc_u32 s99, s19, 0
	s_add_u32 s100, s98, 0x4000000
	s_addc_u32 s101, s99, 0
	s_add_u32 s30, s20, s64
	s_addc_u32 s31, s21, 0
	s_mov_b32 vcc_lo, 0x3d800000
	s_mov_b32 vcc_hi, 0x3d800000
	v_pk_mul_f32 v[128:129], v[124:125], s[42:43] op_sel_hi:[1,0]
	v_pk_mul_f32 v[130:131], v[126:127], s[42:43] op_sel_hi:[1,0]
	v_pk_mul_f32 v[132:133], v[120:121], s[42:43] op_sel_hi:[1,0]
	v_pk_mul_f32 v[134:135], v[122:123], s[42:43] op_sel_hi:[1,0]
	v_pk_mul_f32 v[136:137], v[112:113], s[42:43] op_sel_hi:[1,0]
	v_pk_mul_f32 v[138:139], v[114:115], s[42:43] op_sel_hi:[1,0]
	v_pk_mul_f32 v[116:117], v[116:117], vcc op_sel_hi:[1,0]
	v_pk_mul_f32 v[118:119], v[118:119], vcc op_sel_hi:[1,0]
	v_exp_f32_e32 v128, v128
	v_exp_f32_e32 v129, v129
	v_exp_f32_e32 v130, v130
	v_exp_f32_e32 v131, v131
	v_exp_f32_e32 v132, v132
	v_exp_f32_e32 v133, v133
	v_exp_f32_e32 v134, v134
	v_exp_f32_e32 v135, v135
	v_exp_f32_e32 v136, v136
	v_exp_f32_e32 v137, v137
	v_exp_f32_e32 v138, v138
	v_exp_f32_e32 v139, v139
	v_pk_add_f32 v[128:129], v[128:129], s[42:43] op_sel:[0,1] op_sel_hi:[1,1]
	v_pk_add_f32 v[130:131], v[130:131], s[42:43] op_sel:[0,1] op_sel_hi:[1,1]
	v_pk_add_f32 v[132:133], v[132:133], s[42:43] op_sel:[0,1] op_sel_hi:[1,1]
	v_pk_add_f32 v[134:135], v[134:135], s[42:43] op_sel:[0,1] op_sel_hi:[1,1]
	v_pk_add_f32 v[136:137], v[136:137], s[42:43] op_sel:[0,1] op_sel_hi:[1,1]
	v_pk_add_f32 v[138:139], v[138:139], s[42:43] op_sel:[0,1] op_sel_hi:[1,1]
	v_rcp_f32_e32 v128, v128
	v_rcp_f32_e32 v129, v129
	v_rcp_f32_e32 v130, v130
	v_rcp_f32_e32 v131, v131
	v_rcp_f32_e32 v176, v132
	v_rcp_f32_e32 v177, v133
	v_rcp_f32_e32 v178, v134
	v_rcp_f32_e32 v179, v135
	v_rcp_f32_e32 v180, v136
	v_rcp_f32_e32 v181, v137
	v_rcp_f32_e32 v182, v138
	v_rcp_f32_e32 v183, v139
	v_min_f32_e32 v132, 0x7149f2ca, v132
	v_min_f32_e32 v133, 0x7149f2ca, v133
	v_min_f32_e32 v134, 0x7149f2ca, v134
	v_min_f32_e32 v135, 0x7149f2ca, v135
	v_min_f32_e32 v136, 0x7149f2ca, v136
	v_min_f32_e32 v137, 0x7149f2ca, v137
	v_min_f32_e32 v138, 0x7149f2ca, v138
	v_min_f32_e32 v139, 0x7149f2ca, v139
	v_pk_mul_f32 v[128:129], v[128:129], v[132:133]
	v_pk_mul_f32 v[130:131], v[130:131], v[134:135]
	v_pk_mul_f32 v[176:177], v[176:177], v[136:137]
	v_pk_mul_f32 v[178:179], v[178:179], v[138:139]
	v_cvt_pk_bf16_f32 v198, v116, v117
	v_cvt_pk_bf16_f32 v199, v118, v119
	v_cvt_pk_bf16_f32 v188, v180, v181
	v_cvt_pk_bf16_f32 v189, v182, v183
	v_cvt_pk_bf16_f32 v184, v128, v129
	v_cvt_pk_bf16_f32 v185, v130, v131
	v_cvt_pk_bf16_f32 v186, v176, v177
	v_cvt_pk_bf16_f32 v187, v178, v179
	global_store_dwordx2 v243, v[184:185], s[98:99] nt
	global_store_dwordx2 v243, v[186:187], s[100:101] nt
	global_store_dwordx2 v243, v[188:189], s[30:31] nt
	s_add_u32 s98, s98, 0x800
	s_addc_u32 s99, s99, 0
	s_add_u32 s100, s100, 0x800
	s_addc_u32 s101, s101, 0
	s_add_u32 s30, s30, 0x800
	s_addc_u32 s31, s31, 0
	v_pk_mul_f32 v[128:129], v[108:109], s[42:43] op_sel_hi:[1,0]
	v_pk_mul_f32 v[130:131], v[110:111], s[42:43] op_sel_hi:[1,0]
	v_pk_mul_f32 v[132:133], v[104:105], s[42:43] op_sel_hi:[1,0]
	v_pk_mul_f32 v[134:135], v[106:107], s[42:43] op_sel_hi:[1,0]
	v_pk_mul_f32 v[136:137], v[80:81], s[42:43] op_sel_hi:[1,0]
	v_pk_mul_f32 v[138:139], v[82:83], s[42:43] op_sel_hi:[1,0]
	v_pk_mul_f32 v[84:85], v[84:85], vcc op_sel_hi:[1,0]
	v_pk_mul_f32 v[86:87], v[86:87], vcc op_sel_hi:[1,0]
	v_exp_f32_e32 v128, v128
	v_exp_f32_e32 v129, v129
	v_exp_f32_e32 v130, v130
	v_exp_f32_e32 v131, v131
	v_exp_f32_e32 v132, v132
	v_exp_f32_e32 v133, v133
	v_exp_f32_e32 v134, v134
	v_exp_f32_e32 v135, v135
	v_exp_f32_e32 v136, v136
	v_exp_f32_e32 v137, v137
	v_exp_f32_e32 v138, v138
	v_exp_f32_e32 v139, v139
	v_pk_add_f32 v[128:129], v[128:129], s[42:43] op_sel:[0,1] op_sel_hi:[1,1]
	v_pk_add_f32 v[130:131], v[130:131], s[42:43] op_sel:[0,1] op_sel_hi:[1,1]
	v_pk_add_f32 v[132:133], v[132:133], s[42:43] op_sel:[0,1] op_sel_hi:[1,1]
	v_pk_add_f32 v[134:135], v[134:135], s[42:43] op_sel:[0,1] op_sel_hi:[1,1]
	v_pk_add_f32 v[136:137], v[136:137], s[42:43] op_sel:[0,1] op_sel_hi:[1,1]
; __device__ __forceinline__ float sigmoidf_(float x) { return __builtin_amdgcn_rcpf(1.0f + __builtin_amdgcn_exp2f(-1.44269504089f * x)); }
; __device__ __forceinline__ u32x2 pk4(f32x4 v) { u32x2 r; r.x = pk_bf16(v[0], v[1]); r.y = pk_bf16(v[2], v[3]); return r; }
; __device__ __forceinline__ int pf(int fq) { return (fq >> 1) | ((fq & 1) << 1); }
;     __device__ __forceinline__ void operator()(const f32x4 (&acc)[2][2][4][2], const Unit& u, int wr, int wc, int fr, int fq) const {
;     ...
;                     for (int m = 0; m < 4; ++m) {
;                         const f32x4 Qv = acc[ai][0][m][0], Ga = acc[ai][0][m][1], Gb = acc[ai][1][m][0], Gx = acc[ai][1][m][1]; f32x4 o1, o2, o3;
; #pragma unroll
;                         for (int j = 0; j < 4; ++j) { const float sa = sigmoidf_(Ga[j]), sb = sigmoidf_(Gb[j]), sx = sigmoidf_(Gx[j]);
;                             o1[j] = sa * __builtin_amdgcn_rcpf(fmaxf(sb, 1e-30f)); o2[j] = sb * __builtin_amdgcn_rcpf(fmaxf(sx, 1e-30f)); o3[j] = sx; }
;                         qv[m] = pk4(Qv * 0.0625f);
;                         const int c = (u.pn & 3) * 64 + wc * 16;
;                         const size_t ns = native_slot(u.pm, (u.pn & 15) >> 2, wr * 4 + ((c >> 5) & 3), ai, m, c >> 7, (c >> 4) & 1, pf(fq) * 16 + fr);
;                         __builtin_nontemporal_store(pk4(o1), (u32x2*)SGA + ns); __builtin_nontemporal_store(pk4(o2), (u32x2*)SGB + ns); __builtin_nontemporal_store(pk4(o3), (u32x2*)SGX + ns);
;                     }
	v_pk_add_f32 v[138:139], v[138:139], s[42:43] op_sel:[0,1] op_sel_hi:[1,1]
	v_rcp_f32_e32 v128, v128
	v_rcp_f32_e32 v129, v129
	v_rcp_f32_e32 v130, v130
	v_rcp_f32_e32 v131, v131
	v_rcp_f32_e32 v176, v132
	v_rcp_f32_e32 v177, v133
	v_rcp_f32_e32 v178, v134
	v_rcp_f32_e32 v179, v135
	v_rcp_f32_e32 v180, v136
	v_rcp_f32_e32 v181, v137
	v_rcp_f32_e32 v182, v138
	v_rcp_f32_e32 v183, v139
	v_min_f32_e32 v132, 0x7149f2ca, v132
	v_min_f32_e32 v133, 0x7149f2ca, v133
	v_min_f32_e32 v134, 0x7149f2ca, v134
	v_min_f32_e32 v135, 0x7149f2ca, v135
	v_min_f32_e32 v136, 0x7149f2ca, v136
	v_min_f32_e32 v137, 0x7149f2ca, v137
	v_min_f32_e32 v138, 0x7149f2ca, v138
	v_min_f32_e32 v139, 0x7149f2ca, v139
	v_pk_mul_f32 v[128:129], v[128:129], v[132:133]
	v_pk_mul_f32 v[130:131], v[130:131], v[134:135]
	v_pk_mul_f32 v[176:177], v[176:177], v[136:137]
	v_pk_mul_f32 v[178:179], v[178:179], v[138:139]
	v_cvt_pk_bf16_f32 v200, v84, v85
	v_cvt_pk_bf16_f32 v201, v86, v87
	v_cvt_pk_bf16_f32 v224, v180, v181
	v_cvt_pk_bf16_f32 v225, v182, v183
	v_cvt_pk_bf16_f32 v220, v128, v129
	v_cvt_pk_bf16_f32 v221, v130, v131
	v_cvt_pk_bf16_f32 v222, v176, v177
	v_cvt_pk_bf16_f32 v223, v178, v179
	global_store_dwordx2 v243, v[220:221], s[98:99] nt
	global_store_dwordx2 v243, v[222:223], s[100:101] nt
	global_store_dwordx2 v243, v[224:225], s[30:31] nt
	s_add_u32 s98, s98, 0x800
	s_addc_u32 s99, s99, 0
	s_add_u32 s100, s100, 0x800
	s_addc_u32 s101, s101, 0
	s_add_u32 s30, s30, 0x800
	s_addc_u32 s31, s31, 0
	v_pk_mul_f32 v[128:129], v[100:101], s[42:43] op_sel_hi:[1,0]
	v_pk_mul_f32 v[130:131], v[102:103], s[42:43] op_sel_hi:[1,0]
	v_pk_mul_f32 v[132:133], v[96:97], s[42:43] op_sel_hi:[1,0]
	v_pk_mul_f32 v[134:135], v[98:99], s[42:43] op_sel_hi:[1,0]
	v_pk_mul_f32 v[136:137], v[72:73], s[42:43] op_sel_hi:[1,0]
	v_pk_mul_f32 v[138:139], v[74:75], s[42:43] op_sel_hi:[1,0]
	v_pk_mul_f32 v[76:77], v[76:77], vcc op_sel_hi:[1,0]
	v_pk_mul_f32 v[78:79], v[78:79], vcc op_sel_hi:[1,0]
	v_exp_f32_e32 v128, v128
	v_exp_f32_e32 v129, v129
	v_exp_f32_e32 v130, v130
	v_exp_f32_e32 v131, v131
	v_exp_f32_e32 v132, v132
	v_exp_f32_e32 v133, v133
	v_exp_f32_e32 v134, v134
	v_exp_f32_e32 v135, v135
	v_exp_f32_e32 v136, v136
	v_exp_f32_e32 v137, v137
	v_exp_f32_e32 v138, v138
	v_exp_f32_e32 v139, v139
	v_pk_add_f32 v[128:129], v[128:129], s[42:43] op_sel:[0,1] op_sel_hi:[1,1]
	v_pk_add_f32 v[130:131], v[130:131], s[42:43] op_sel:[0,1] op_sel_hi:[1,1]
	v_pk_add_f32 v[132:133], v[132:133], s[42:43] op_sel:[0,1] op_sel_hi:[1,1]
	v_pk_add_f32 v[134:135], v[134:135], s[42:43] op_sel:[0,1] op_sel_hi:[1,1]
	v_pk_add_f32 v[136:137], v[136:137], s[42:43] op_sel:[0,1] op_sel_hi:[1,1]
	v_pk_add_f32 v[138:139], v[138:139], s[42:43] op_sel:[0,1] op_sel_hi:[1,1]
	v_rcp_f32_e32 v128, v128
	v_rcp_f32_e32 v129, v129
	v_rcp_f32_e32 v130, v130
	v_rcp_f32_e32 v131, v131
	v_rcp_f32_e32 v176, v132
	v_rcp_f32_e32 v177, v133
	v_rcp_f32_e32 v178, v134
	v_rcp_f32_e32 v179, v135
	v_rcp_f32_e32 v180, v136
	v_rcp_f32_e32 v181, v137
	v_rcp_f32_e32 v182, v138
	v_rcp_f32_e32 v183, v139
	v_min_f32_e32 v132, 0x7149f2ca, v132
	v_min_f32_e32 v133, 0x7149f2ca, v133
	v_min_f32_e32 v134, 0x7149f2ca, v134
	v_min_f32_e32 v135, 0x7149f2ca, v135
	v_min_f32_e32 v136, 0x7149f2ca, v136
	v_min_f32_e32 v137, 0x7149f2ca, v137
	v_min_f32_e32 v138, 0x7149f2ca, v138
	v_min_f32_e32 v139, 0x7149f2ca, v139
	v_pk_mul_f32 v[128:129], v[128:129], v[132:133]
	v_pk_mul_f32 v[130:131], v[130:131], v[134:135]
	v_pk_mul_f32 v[176:177], v[176:177], v[136:137]
	v_pk_mul_f32 v[178:179], v[178:179], v[138:139]
	v_cvt_pk_bf16_f32 v202, v76, v77
	v_cvt_pk_bf16_f32 v203, v78, v79
	v_cvt_pk_bf16_f32 v188, v180, v181
	v_cvt_pk_bf16_f32 v189, v182, v183
	v_cvt_pk_bf16_f32 v184, v128, v129
	v_cvt_pk_bf16_f32 v185, v130, v131
	v_cvt_pk_bf16_f32 v186, v176, v177
	v_cvt_pk_bf16_f32 v187, v178, v179
	global_store_dwordx2 v243, v[184:185], s[98:99] nt
	global_store_dwordx2 v243, v[186:187], s[100:101] nt
	global_store_dwordx2 v243, v[188:189], s[30:31] nt
	s_add_u32 s98, s98, 0x800
	s_addc_u32 s99, s99, 0
	s_add_u32 s100, s100, 0x800
	s_addc_u32 s101, s101, 0
	s_add_u32 s30, s30, 0x800
	s_addc_u32 s31, s31, 0
	v_pk_mul_f32 v[128:129], v[92:93], s[42:43] op_sel_hi:[1,0]
	v_pk_mul_f32 v[130:131], v[94:95], s[42:43] op_sel_hi:[1,0]
	v_pk_mul_f32 v[132:133], v[88:89], s[42:43] op_sel_hi:[1,0]
	v_pk_mul_f32 v[134:135], v[90:91], s[42:43] op_sel_hi:[1,0]
	v_pk_mul_f32 v[136:137], v[64:65], s[42:43] op_sel_hi:[1,0]
	v_pk_mul_f32 v[138:139], v[66:67], s[42:43] op_sel_hi:[1,0]
	v_pk_mul_f32 v[68:69], v[68:69], vcc op_sel_hi:[1,0]
	v_pk_mul_f32 v[70:71], v[70:71], vcc op_sel_hi:[1,0]
	v_exp_f32_e32 v128, v128
	v_exp_f32_e32 v129, v129
	v_exp_f32_e32 v130, v130
	v_exp_f32_e32 v131, v131
	v_exp_f32_e32 v132, v132
	v_exp_f32_e32 v133, v133
	v_exp_f32_e32 v134, v134
	v_exp_f32_e32 v135, v135
	v_exp_f32_e32 v136, v136
	v_exp_f32_e32 v137, v137
	v_exp_f32_e32 v138, v138
	v_exp_f32_e32 v139, v139
	v_pk_add_f32 v[128:129], v[128:129], s[42:43] op_sel:[0,1] op_sel_hi:[1,1]
	v_pk_add_f32 v[130:131], v[130:131], s[42:43] op_sel:[0,1] op_sel_hi:[1,1]
	v_pk_add_f32 v[132:133], v[132:133], s[42:43] op_sel:[0,1] op_sel_hi:[1,1]
	v_pk_add_f32 v[134:135], v[134:135], s[42:43] op_sel:[0,1] op_sel_hi:[1,1]
	v_pk_add_f32 v[136:137], v[136:137], s[42:43] op_sel:[0,1] op_sel_hi:[1,1]
	v_pk_add_f32 v[138:139], v[138:139], s[42:43] op_sel:[0,1] op_sel_hi:[1,1]
	v_rcp_f32_e32 v128, v128
	v_rcp_f32_e32 v129, v129
	v_rcp_f32_e32 v130, v130
	v_rcp_f32_e32 v131, v131
	v_rcp_f32_e32 v176, v132
	v_rcp_f32_e32 v177, v133
	v_rcp_f32_e32 v178, v134
	v_rcp_f32_e32 v179, v135
	v_rcp_f32_e32 v180, v136
	v_rcp_f32_e32 v181, v137
; __device__ __forceinline__ float sigmoidf_(float x) { return __builtin_amdgcn_rcpf(1.0f + __builtin_amdgcn_exp2f(-1.44269504089f * x)); }
; __device__ __forceinline__ u32x2 pk4(f32x4 v) { u32x2 r; r.x = pk_bf16(v[0], v[1]); r.y = pk_bf16(v[2], v[3]); return r; }
; __device__ __forceinline__ int pf(int fq) { return (fq >> 1) | ((fq & 1) << 1); }
;     __device__ __forceinline__ void operator()(const f32x4 (&acc)[2][2][4][2], const Unit& u, int wr, int wc, int fr, int fq) const {
;     ...
;                 for (int ai = 0; ai < 2; ++ai) {
;                     u32x2 qv[4];
; #pragma unroll
;                     for (int m = 0; m < 4; ++m) {
;                         const f32x4 Qv = acc[ai][0][m][0], Ga = acc[ai][0][m][1], Gb = acc[ai][1][m][0], Gx = acc[ai][1][m][1]; f32x4 o1, o2, o3;
; #pragma unroll
;                         for (int j = 0; j < 4; ++j) { const float sa = sigmoidf_(Ga[j]), sb = sigmoidf_(Gb[j]), sx = sigmoidf_(Gx[j]);
;                             o1[j] = sa * __builtin_amdgcn_rcpf(fmaxf(sb, 1e-30f)); o2[j] = sb * __builtin_amdgcn_rcpf(fmaxf(sx, 1e-30f)); o3[j] = sx; }
;                         qv[m] = pk4(Qv * 0.0625f);
;                         const int c = (u.pn & 3) * 64 + wc * 16;
;                         const size_t ns = native_slot(u.pm, (u.pn & 15) >> 2, wr * 4 + ((c >> 5) & 3), ai, m, c >> 7, (c >> 4) & 1, pf(fq) * 16 + fr);
;                         __builtin_nontemporal_store(pk4(o1), (u32x2*)SGA + ns); __builtin_nontemporal_store(pk4(o2), (u32x2*)SGB + ns); __builtin_nontemporal_store(pk4(o3), (u32x2*)SGX + ns);
;                     }
; #pragma unroll
;                     for (int pr = 0; pr < 2; ++pr) store_pair16(Q + (size_t)(rowb + ai * 128 + pr * 32) * 1024 + chw, qv[2 * pr], qv[2 * pr + 1], fq);
	v_rcp_f32_e32 v182, v138
	v_rcp_f32_e32 v183, v139
	v_min_f32_e32 v132, 0x7149f2ca, v132
	v_min_f32_e32 v133, 0x7149f2ca, v133
	v_min_f32_e32 v134, 0x7149f2ca, v134
	v_min_f32_e32 v135, 0x7149f2ca, v135
	v_min_f32_e32 v136, 0x7149f2ca, v136
	v_min_f32_e32 v137, 0x7149f2ca, v137
	v_min_f32_e32 v138, 0x7149f2ca, v138
	v_min_f32_e32 v139, 0x7149f2ca, v139
	v_pk_mul_f32 v[128:129], v[128:129], v[132:133]
	v_pk_mul_f32 v[130:131], v[130:131], v[134:135]
	v_pk_mul_f32 v[176:177], v[176:177], v[136:137]
	v_pk_mul_f32 v[178:179], v[178:179], v[138:139]
	v_cvt_pk_bf16_f32 v204, v68, v69
	v_cvt_pk_bf16_f32 v205, v70, v71
	v_cvt_pk_bf16_f32 v224, v180, v181
	v_cvt_pk_bf16_f32 v225, v182, v183
	v_cvt_pk_bf16_f32 v220, v128, v129
	v_cvt_pk_bf16_f32 v221, v130, v131
	v_cvt_pk_bf16_f32 v222, v176, v177
	v_cvt_pk_bf16_f32 v223, v178, v179
	global_store_dwordx2 v243, v[220:221], s[98:99] nt
	global_store_dwordx2 v243, v[222:223], s[100:101] nt
	global_store_dwordx2 v243, v[224:225], s[30:31] nt
	s_add_u32 s98, s98, 0x800
	s_addc_u32 s99, s99, 0
	s_add_u32 s100, s100, 0x800
	s_addc_u32 s101, s101, 0
	s_add_u32 s30, s30, 0x800
	s_addc_u32 s31, s31, 0
	s_nop 1
	v_permlane32_swap_b32_e32 v198, v200
	v_permlane32_swap_b32_e32 v199, v201
	v_lshl_add_u64 v[248:249], s[46:47], 0, v[246:247]
	global_store_dwordx4 v[248:249], v[198:201], off
	s_nop 1
	v_permlane32_swap_b32_e32 v202, v204
	v_permlane32_swap_b32_e32 v203, v205
	s_mov_b64 s[4:5], 0x10000
	v_lshl_add_u64 v[248:249], v[246:247], 0, s[4:5]
	v_lshl_add_u64 v[248:249], s[46:47], 0, v[248:249]
	global_store_dwordx4 v[248:249], v[202:205], off
	v_pk_mul_f32 v[128:129], v[60:61], s[42:43] op_sel_hi:[1,0]
	v_pk_mul_f32 v[130:131], v[62:63], s[42:43] op_sel_hi:[1,0]
	v_pk_mul_f32 v[132:133], v[56:57], s[42:43] op_sel_hi:[1,0]
	v_pk_mul_f32 v[134:135], v[58:59], s[42:43] op_sel_hi:[1,0]
	v_pk_mul_f32 v[136:137], v[48:49], s[42:43] op_sel_hi:[1,0]
	v_pk_mul_f32 v[138:139], v[50:51], s[42:43] op_sel_hi:[1,0]
	v_pk_mul_f32 v[52:53], v[52:53], vcc op_sel_hi:[1,0]
	v_pk_mul_f32 v[54:55], v[54:55], vcc op_sel_hi:[1,0]
	v_exp_f32_e32 v128, v128
	v_exp_f32_e32 v129, v129
	v_exp_f32_e32 v130, v130
	v_exp_f32_e32 v131, v131
	v_exp_f32_e32 v132, v132
	v_exp_f32_e32 v133, v133
	v_exp_f32_e32 v134, v134
	v_exp_f32_e32 v135, v135
	v_exp_f32_e32 v136, v136
	v_exp_f32_e32 v137, v137
	v_exp_f32_e32 v138, v138
	v_exp_f32_e32 v139, v139
	v_pk_add_f32 v[128:129], v[128:129], s[42:43] op_sel:[0,1] op_sel_hi:[1,1]
	v_pk_add_f32 v[130:131], v[130:131], s[42:43] op_sel:[0,1] op_sel_hi:[1,1]
	v_pk_add_f32 v[132:133], v[132:133], s[42:43] op_sel:[0,1] op_sel_hi:[1,1]
	v_pk_add_f32 v[134:135], v[134:135], s[42:43] op_sel:[0,1] op_sel_hi:[1,1]
	v_pk_add_f32 v[136:137], v[136:137], s[42:43] op_sel:[0,1] op_sel_hi:[1,1]
	v_pk_add_f32 v[138:139], v[138:139], s[42:43] op_sel:[0,1] op_sel_hi:[1,1]
	v_rcp_f32_e32 v128, v128
	v_rcp_f32_e32 v129, v129
	v_rcp_f32_e32 v130, v130
	v_rcp_f32_e32 v131, v131
	v_rcp_f32_e32 v176, v132
	v_rcp_f32_e32 v177, v133
	v_rcp_f32_e32 v178, v134
	v_rcp_f32_e32 v179, v135
	v_rcp_f32_e32 v180, v136
	v_rcp_f32_e32 v181, v137
	v_rcp_f32_e32 v182, v138
	v_rcp_f32_e32 v183, v139
	v_min_f32_e32 v132, 0x7149f2ca, v132
	v_min_f32_e32 v133, 0x7149f2ca, v133
	v_min_f32_e32 v134, 0x7149f2ca, v134
	v_min_f32_e32 v135, 0x7149f2ca, v135
	v_min_f32_e32 v136, 0x7149f2ca, v136
	v_min_f32_e32 v137, 0x7149f2ca, v137
	v_min_f32_e32 v138, 0x7149f2ca, v138
	v_min_f32_e32 v139, 0x7149f2ca, v139
	v_pk_mul_f32 v[128:129], v[128:129], v[132:133]
	v_pk_mul_f32 v[130:131], v[130:131], v[134:135]
	v_pk_mul_f32 v[176:177], v[176:177], v[136:137]
	v_pk_mul_f32 v[178:179], v[178:179], v[138:139]
	v_cvt_pk_bf16_f32 v198, v52, v53
	v_cvt_pk_bf16_f32 v199, v54, v55
	v_cvt_pk_bf16_f32 v188, v180, v181
	v_cvt_pk_bf16_f32 v189, v182, v183
	v_cvt_pk_bf16_f32 v184, v128, v129
	v_cvt_pk_bf16_f32 v185, v130, v131
	v_cvt_pk_bf16_f32 v186, v176, v177
	v_cvt_pk_bf16_f32 v187, v178, v179
	global_store_dwordx2 v243, v[184:185], s[98:99] nt
	global_store_dwordx2 v243, v[186:187], s[100:101] nt
	global_store_dwordx2 v243, v[188:189], s[30:31] nt
	s_add_u32 s98, s98, 0x800
	s_addc_u32 s99, s99, 0
	s_add_u32 s100, s100, 0x800
	s_addc_u32 s101, s101, 0
	s_add_u32 s30, s30, 0x800
	s_addc_u32 s31, s31, 0
	v_pk_mul_f32 v[128:129], v[44:45], s[42:43] op_sel_hi:[1,0]
	v_pk_mul_f32 v[130:131], v[46:47], s[42:43] op_sel_hi:[1,0]
	v_pk_mul_f32 v[132:133], v[40:41], s[42:43] op_sel_hi:[1,0]
	v_pk_mul_f32 v[134:135], v[42:43], s[42:43] op_sel_hi:[1,0]
	v_pk_mul_f32 v[136:137], v[16:17], s[42:43] op_sel_hi:[1,0]
	v_pk_mul_f32 v[138:139], v[18:19], s[42:43] op_sel_hi:[1,0]
	v_pk_mul_f32 v[20:21], v[20:21], vcc op_sel_hi:[1,0]
	v_pk_mul_f32 v[22:23], v[22:23], vcc op_sel_hi:[1,0]
	v_exp_f32_e32 v128, v128
	v_exp_f32_e32 v129, v129
	v_exp_f32_e32 v130, v130
	v_exp_f32_e32 v131, v131
	v_exp_f32_e32 v132, v132
	v_exp_f32_e32 v133, v133
	v_exp_f32_e32 v134, v134
	v_exp_f32_e32 v135, v135
	v_exp_f32_e32 v136, v136
	v_exp_f32_e32 v137, v137
	v_exp_f32_e32 v138, v138
	v_exp_f32_e32 v139, v139
	v_pk_add_f32 v[128:129], v[128:129], s[42:43] op_sel:[0,1] op_sel_hi:[1,1]
	v_pk_add_f32 v[130:131], v[130:131], s[42:43] op_sel:[0,1] op_sel_hi:[1,1]
	v_pk_add_f32 v[132:133], v[132:133], s[42:43] op_sel:[0,1] op_sel_hi:[1,1]
	v_pk_add_f32 v[134:135], v[134:135], s[42:43] op_sel:[0,1] op_sel_hi:[1,1]
	v_pk_add_f32 v[136:137], v[136:137], s[42:43] op_sel:[0,1] op_sel_hi:[1,1]
	v_pk_add_f32 v[138:139], v[138:139], s[42:43] op_sel:[0,1] op_sel_hi:[1,1]
	v_rcp_f32_e32 v128, v128
	v_rcp_f32_e32 v129, v129
	v_rcp_f32_e32 v130, v130
	v_rcp_f32_e32 v131, v131
	v_rcp_f32_e32 v176, v132
; __device__ __forceinline__ float sigmoidf_(float x) { return __builtin_amdgcn_rcpf(1.0f + __builtin_amdgcn_exp2f(-1.44269504089f * x)); }
; __device__ __forceinline__ u32x2 pk4(f32x4 v) { u32x2 r; r.x = pk_bf16(v[0], v[1]); r.y = pk_bf16(v[2], v[3]); return r; }
; __device__ __forceinline__ int pf(int fq) { return (fq >> 1) | ((fq & 1) << 1); }
;     __device__ __forceinline__ void operator()(const f32x4 (&acc)[2][2][4][2], const Unit& u, int wr, int wc, int fr, int fq) const {
;     ...
;                     for (int m = 0; m < 4; ++m) {
;                         const f32x4 Qv = acc[ai][0][m][0], Ga = acc[ai][0][m][1], Gb = acc[ai][1][m][0], Gx = acc[ai][1][m][1]; f32x4 o1, o2, o3;
; #pragma unroll
;                         for (int j = 0; j < 4; ++j) { const float sa = sigmoidf_(Ga[j]), sb = sigmoidf_(Gb[j]), sx = sigmoidf_(Gx[j]);
;                             o1[j] = sa * __builtin_amdgcn_rcpf(fmaxf(sb, 1e-30f)); o2[j] = sb * __builtin_amdgcn_rcpf(fmaxf(sx, 1e-30f)); o3[j] = sx; }
;                         qv[m] = pk4(Qv * 0.0625f);
;                         const int c = (u.pn & 3) * 64 + wc * 16;
;                         const size_t ns = native_slot(u.pm, (u.pn & 15) >> 2, wr * 4 + ((c >> 5) & 3), ai, m, c >> 7, (c >> 4) & 1, pf(fq) * 16 + fr);
;                         __builtin_nontemporal_store(pk4(o1), (u32x2*)SGA + ns); __builtin_nontemporal_store(pk4(o2), (u32x2*)SGB + ns); __builtin_nontemporal_store(pk4(o3), (u32x2*)SGX + ns);
;                     }
	v_rcp_f32_e32 v177, v133
	v_rcp_f32_e32 v178, v134
	v_rcp_f32_e32 v179, v135
	v_rcp_f32_e32 v180, v136
	v_rcp_f32_e32 v181, v137
	v_rcp_f32_e32 v182, v138
	v_rcp_f32_e32 v183, v139
	v_min_f32_e32 v132, 0x7149f2ca, v132
	v_min_f32_e32 v133, 0x7149f2ca, v133
	v_min_f32_e32 v134, 0x7149f2ca, v134
	v_min_f32_e32 v135, 0x7149f2ca, v135
	v_min_f32_e32 v136, 0x7149f2ca, v136
	v_min_f32_e32 v137, 0x7149f2ca, v137
	v_min_f32_e32 v138, 0x7149f2ca, v138
	v_min_f32_e32 v139, 0x7149f2ca, v139
	v_pk_mul_f32 v[128:129], v[128:129], v[132:133]
	v_pk_mul_f32 v[130:131], v[130:131], v[134:135]
	v_pk_mul_f32 v[176:177], v[176:177], v[136:137]
	v_pk_mul_f32 v[178:179], v[178:179], v[138:139]
	v_cvt_pk_bf16_f32 v200, v20, v21
	v_cvt_pk_bf16_f32 v201, v22, v23
	v_cvt_pk_bf16_f32 v224, v180, v181
	v_cvt_pk_bf16_f32 v225, v182, v183
	v_cvt_pk_bf16_f32 v220, v128, v129
	v_cvt_pk_bf16_f32 v221, v130, v131
	v_cvt_pk_bf16_f32 v222, v176, v177
	v_cvt_pk_bf16_f32 v223, v178, v179
	global_store_dwordx2 v243, v[220:221], s[98:99] nt
	global_store_dwordx2 v243, v[222:223], s[100:101] nt
	global_store_dwordx2 v243, v[224:225], s[30:31] nt
	s_add_u32 s98, s98, 0x800
	s_addc_u32 s99, s99, 0
	s_add_u32 s100, s100, 0x800
	s_addc_u32 s101, s101, 0
	s_add_u32 s30, s30, 0x800
	s_addc_u32 s31, s31, 0
	v_pk_mul_f32 v[128:129], v[36:37], s[42:43] op_sel_hi:[1,0]
	v_pk_mul_f32 v[130:131], v[38:39], s[42:43] op_sel_hi:[1,0]
	v_pk_mul_f32 v[132:133], v[32:33], s[42:43] op_sel_hi:[1,0]
	v_pk_mul_f32 v[134:135], v[34:35], s[42:43] op_sel_hi:[1,0]
	v_pk_mul_f32 v[136:137], v[8:9], s[42:43] op_sel_hi:[1,0]
	v_pk_mul_f32 v[138:139], v[10:11], s[42:43] op_sel_hi:[1,0]
	v_pk_mul_f32 v[12:13], v[12:13], vcc op_sel_hi:[1,0]
	v_pk_mul_f32 v[14:15], v[14:15], vcc op_sel_hi:[1,0]
	v_exp_f32_e32 v128, v128
	v_exp_f32_e32 v129, v129
	v_exp_f32_e32 v130, v130
	v_exp_f32_e32 v131, v131
	v_exp_f32_e32 v132, v132
	v_exp_f32_e32 v133, v133
	v_exp_f32_e32 v134, v134
	v_exp_f32_e32 v135, v135
	v_exp_f32_e32 v136, v136
	v_exp_f32_e32 v137, v137
	v_exp_f32_e32 v138, v138
	v_exp_f32_e32 v139, v139
	v_pk_add_f32 v[128:129], v[128:129], s[42:43] op_sel:[0,1] op_sel_hi:[1,1]
	v_pk_add_f32 v[130:131], v[130:131], s[42:43] op_sel:[0,1] op_sel_hi:[1,1]
	v_pk_add_f32 v[132:133], v[132:133], s[42:43] op_sel:[0,1] op_sel_hi:[1,1]
	v_pk_add_f32 v[134:135], v[134:135], s[42:43] op_sel:[0,1] op_sel_hi:[1,1]
	v_pk_add_f32 v[136:137], v[136:137], s[42:43] op_sel:[0,1] op_sel_hi:[1,1]
	v_pk_add_f32 v[138:139], v[138:139], s[42:43] op_sel:[0,1] op_sel_hi:[1,1]
	v_rcp_f32_e32 v128, v128
	v_rcp_f32_e32 v129, v129
	v_rcp_f32_e32 v130, v130
	v_rcp_f32_e32 v131, v131
	v_rcp_f32_e32 v176, v132
	v_rcp_f32_e32 v177, v133
	v_rcp_f32_e32 v178, v134
	v_rcp_f32_e32 v179, v135
	v_rcp_f32_e32 v180, v136
	v_rcp_f32_e32 v181, v137
	v_rcp_f32_e32 v182, v138
	v_rcp_f32_e32 v183, v139
	v_min_f32_e32 v132, 0x7149f2ca, v132
	v_min_f32_e32 v133, 0x7149f2ca, v133
	v_min_f32_e32 v134, 0x7149f2ca, v134
	v_min_f32_e32 v135, 0x7149f2ca, v135
	v_min_f32_e32 v136, 0x7149f2ca, v136
	v_min_f32_e32 v137, 0x7149f2ca, v137
	v_min_f32_e32 v138, 0x7149f2ca, v138
	v_min_f32_e32 v139, 0x7149f2ca, v139
	v_pk_mul_f32 v[128:129], v[128:129], v[132:133]
	v_pk_mul_f32 v[130:131], v[130:131], v[134:135]
	v_pk_mul_f32 v[176:177], v[176:177], v[136:137]
	v_pk_mul_f32 v[178:179], v[178:179], v[138:139]
	v_cvt_pk_bf16_f32 v202, v12, v13
	v_cvt_pk_bf16_f32 v203, v14, v15
	v_cvt_pk_bf16_f32 v188, v180, v181
	v_cvt_pk_bf16_f32 v189, v182, v183
	v_cvt_pk_bf16_f32 v184, v128, v129
	v_cvt_pk_bf16_f32 v185, v130, v131
	v_cvt_pk_bf16_f32 v186, v176, v177
	v_cvt_pk_bf16_f32 v187, v178, v179
	global_store_dwordx2 v243, v[184:185], s[98:99] nt
	global_store_dwordx2 v243, v[186:187], s[100:101] nt
	global_store_dwordx2 v243, v[188:189], s[30:31] nt
	s_add_u32 s98, s98, 0x800
	s_addc_u32 s99, s99, 0
	s_add_u32 s100, s100, 0x800
	s_addc_u32 s101, s101, 0
	s_add_u32 s30, s30, 0x800
	s_addc_u32 s31, s31, 0
	v_pk_mul_f32 v[128:129], v[28:29], s[42:43] op_sel_hi:[1,0]
	v_pk_mul_f32 v[130:131], v[30:31], s[42:43] op_sel_hi:[1,0]
	v_pk_mul_f32 v[132:133], v[24:25], s[42:43] op_sel_hi:[1,0]
	v_pk_mul_f32 v[134:135], v[26:27], s[42:43] op_sel_hi:[1,0]
	v_pk_mul_f32 v[136:137], v[0:1], s[42:43] op_sel_hi:[1,0]
	v_pk_mul_f32 v[138:139], v[2:3], s[42:43] op_sel_hi:[1,0]
	v_pk_mul_f32 v[4:5], v[4:5], vcc op_sel_hi:[1,0]
	v_pk_mul_f32 v[6:7], v[6:7], vcc op_sel_hi:[1,0]
	v_exp_f32_e32 v128, v128
	v_exp_f32_e32 v129, v129
	v_exp_f32_e32 v130, v130
	v_exp_f32_e32 v131, v131
	v_exp_f32_e32 v132, v132
	v_exp_f32_e32 v133, v133
	v_exp_f32_e32 v134, v134
	v_exp_f32_e32 v135, v135
	v_exp_f32_e32 v136, v136
	v_exp_f32_e32 v137, v137
	v_exp_f32_e32 v138, v138
	v_exp_f32_e32 v139, v139
	v_pk_add_f32 v[128:129], v[128:129], s[42:43] op_sel:[0,1] op_sel_hi:[1,1]
	v_pk_add_f32 v[130:131], v[130:131], s[42:43] op_sel:[0,1] op_sel_hi:[1,1]
	v_pk_add_f32 v[132:133], v[132:133], s[42:43] op_sel:[0,1] op_sel_hi:[1,1]
	v_pk_add_f32 v[134:135], v[134:135], s[42:43] op_sel:[0,1] op_sel_hi:[1,1]
	v_pk_add_f32 v[136:137], v[136:137], s[42:43] op_sel:[0,1] op_sel_hi:[1,1]
	v_pk_add_f32 v[138:139], v[138:139], s[42:43] op_sel:[0,1] op_sel_hi:[1,1]
	v_rcp_f32_e32 v128, v128
	v_rcp_f32_e32 v129, v129
	v_rcp_f32_e32 v130, v130
	v_rcp_f32_e32 v131, v131
	v_rcp_f32_e32 v176, v132
	v_rcp_f32_e32 v177, v133
	v_rcp_f32_e32 v178, v134
	v_rcp_f32_e32 v179, v135
	v_rcp_f32_e32 v180, v136
	v_rcp_f32_e32 v181, v137
	v_rcp_f32_e32 v182, v138
	v_rcp_f32_e32 v183, v139
	v_min_f32_e32 v132, 0x7149f2ca, v132
	v_min_f32_e32 v133, 0x7149f2ca, v133
	v_min_f32_e32 v134, 0x7149f2ca, v134
	v_min_f32_e32 v135, 0x7149f2ca, v135
; __device__ __forceinline__ float sigmoidf_(float x) { return __builtin_amdgcn_rcpf(1.0f + __builtin_amdgcn_exp2f(-1.44269504089f * x)); }
;     __device__ __forceinline__ void operator()(const f32x4 (&acc)[2][2][4][2], const Unit& u, int wr, int wc, int fr, int fq) const {
;     ...
;                 for (int ai = 0; ai < 2; ++ai) {
;                     u32x2 gv[4], zv[4];
; #pragma unroll
;                     for (int m = 0; m < 4; ++m) {
;                         const f32x4 Vv = acc[ai][0][m][0], Gv = acc[ai][0][m][1], Zb = acc[ai][1][m][0], Zx = acc[ai][1][m][1]; f32x4 o0, o1, o2;
; #pragma unroll
;                         for (int j = 0; j < 4; ++j) { o0[j] = Vv[j] * sigmoidf_(Gv[j]); o1[j] = siluf_(Zb[j]); o2[j] = siluf_(Zx[j]); }
;                         gv[m] = pk4(o0); zv[m] = pk4(o1);
;                         { const int c = (u.pn & 3) * 64 + wc * 16;
;                           __builtin_nontemporal_store(pk4(o2), (u32x2*)SZX + native_slot(u.pm, (u.pn & 15) >> 2, wr * 4 + ((c >> 5) & 3), ai, m, c >> 7, (c >> 4) & 1, pf(fq) * 16 + fr)); }
;                     }
;     ...
;                 for (int ai = 0; ai < 2; ++ai) {
;                     u32x2 qv[4];
; #pragma unroll
;                     for (int m = 0; m < 4; ++m) {
;                         const f32x4 Qv = acc[ai][0][m][0], Ga = acc[ai][0][m][1], Gb = acc[ai][1][m][0], Gx = acc[ai][1][m][1]; f32x4 o1, o2, o3;
; #pragma unroll
;                         for (int j = 0; j < 4; ++j) { const float sa = sigmoidf_(Ga[j]), sb = sigmoidf_(Gb[j]), sx = sigmoidf_(Gx[j]);
;                             o1[j] = sa * __builtin_amdgcn_rcpf(fmaxf(sb, 1e-30f)); o2[j] = sb * __builtin_amdgcn_rcpf(fmaxf(sx, 1e-30f)); o3[j] = sx; }
;                         qv[m] = pk4(Qv * 0.0625f);
;                         const int c = (u.pn & 3) * 64 + wc * 16;
;                         const size_t ns = native_slot(u.pm, (u.pn & 15) >> 2, wr * 4 + ((c >> 5) & 3), ai, m, c >> 7, (c >> 4) & 1, pf(fq) * 16 + fr);
;                         __builtin_nontemporal_store(pk4(o1), (u32x2*)SGA + ns); __builtin_nontemporal_store(pk4(o2), (u32x2*)SGB + ns); __builtin_nontemporal_store(pk4(o3), (u32x2*)SGX + ns);
;                     }
; #pragma unroll
;                     for (int pr = 0; pr < 2; ++pr) store_pair16(Q + (size_t)(rowb + ai * 128 + pr * 32) * 1024 + chw, qv[2 * pr], qv[2 * pr + 1], fq);
	v_min_f32_e32 v136, 0x7149f2ca, v136
	v_min_f32_e32 v137, 0x7149f2ca, v137
	v_min_f32_e32 v138, 0x7149f2ca, v138
	v_min_f32_e32 v139, 0x7149f2ca, v139
	v_pk_mul_f32 v[128:129], v[128:129], v[132:133]
	v_pk_mul_f32 v[130:131], v[130:131], v[134:135]
	v_pk_mul_f32 v[176:177], v[176:177], v[136:137]
	v_pk_mul_f32 v[178:179], v[178:179], v[138:139]
	v_cvt_pk_bf16_f32 v204, v4, v5
	v_cvt_pk_bf16_f32 v205, v6, v7
	v_cvt_pk_bf16_f32 v224, v180, v181
	v_cvt_pk_bf16_f32 v225, v182, v183
	v_cvt_pk_bf16_f32 v220, v128, v129
	v_cvt_pk_bf16_f32 v221, v130, v131
	v_cvt_pk_bf16_f32 v222, v176, v177
	v_cvt_pk_bf16_f32 v223, v178, v179
	global_store_dwordx2 v243, v[220:221], s[98:99] nt
	global_store_dwordx2 v243, v[222:223], s[100:101] nt
	global_store_dwordx2 v243, v[224:225], s[30:31] nt
	s_add_u32 s98, s98, 0x800
	s_addc_u32 s99, s99, 0
	s_add_u32 s100, s100, 0x800
	s_addc_u32 s101, s101, 0
	s_add_u32 s30, s30, 0x800
	s_addc_u32 s31, s31, 0
	s_nop 1
	v_permlane32_swap_b32_e32 v198, v200
	v_permlane32_swap_b32_e32 v199, v201
	s_mov_b64 s[4:5], 0x40000
	v_lshl_add_u64 v[248:249], v[246:247], 0, s[4:5]
	v_lshl_add_u64 v[248:249], s[46:47], 0, v[248:249]
	global_store_dwordx4 v[248:249], v[198:201], off
	s_nop 1
	v_permlane32_swap_b32_e32 v202, v204
	v_permlane32_swap_b32_e32 v203, v205
	s_mov_b64 s[4:5], 0x50000
	v_lshl_add_u64 v[248:249], v[246:247], 0, s[4:5]
	v_lshl_add_u64 v[248:249], s[46:47], 0, v[248:249]
	global_store_dwordx4 v[248:249], v[202:205], off
	s_branch .LBB0_287
.Lp1e_k1:
	v_mbcnt_lo_u32_b32 v240, -1, 0
	v_mbcnt_hi_u32_b32 v240, -1, v240
	v_readlane_b32 s4, v255, 19
	s_nop 3
	s_lshr_b32 s4, s4, 6
	s_lshr_b32 s5, s4, 2
	s_and_b32 s30, s4, 3
	v_and_b32_e32 v241, 15, v240
	v_lshrrev_b32_e32 v242, 4, v240
	v_lshrrev_b32_e32 v243, 1, v242
	v_and_b32_e32 v244, 1, v242
	v_lshl_or_b32 v248, v244, 1, v243
	v_lshl_add_u32 v248, v248, 4, v241
	v_lshl_add_u32 v246, v243, 4, v241
	v_lshlrev_b32_e32 v243, 3, v248
	s_lshl_b32 s31, s96, 8
	s_lshl_b32 s64, s5, 6
	s_add_i32 s31, s31, s64
	v_add_u32_e32 v246, s31, v246
	v_mov_b32_e32 v247, 0
	v_lshlrev_b64 v[246:247], 11, v[246:247]
	s_and_b32 s64, s90, 15
	s_lshl_b32 s64, s64, 6
	s_lshl_b32 vcc_lo, s30, 4
	s_add_i32 s64, s64, vcc_lo
	v_lshlrev_b32_e32 v244, 3, v244
	v_add_u32_e32 v244, s64, v244
	v_lshlrev_b32_e32 v244, 1, v244
	v_mov_b32_e32 v245, 0
	v_lshl_add_u64 v[246:247], v[246:247], 0, v[244:245]
	s_lshl_b32 s64, s96, 2
	s_bfe_u32 vcc_lo, s90, 0x20002
	s_add_i32 s64, s64, vcc_lo
	s_lshl_b32 s64, s64, 17
	s_lshl_b32 vcc_lo, s5, 2
	s_and_b32 vcc_hi, s90, 1
	s_lshl_b32 vcc_hi, vcc_hi, 1
	s_add_i32 vcc_lo, vcc_lo, vcc_hi
	s_lshr_b32 vcc_hi, s30, 1
	s_add_i32 vcc_lo, vcc_lo, vcc_hi
	s_lshl_b32 vcc_lo, vcc_lo, 14
	s_add_i32 s64, s64, vcc_lo
	s_bfe_u32 vcc_lo, s90, 0x10001
	s_lshl_b32 vcc_lo, vcc_lo, 1
	s_and_b32 vcc_hi, s30, 1
	s_add_i32 vcc_lo, vcc_lo, vcc_hi
	s_lshl_b32 vcc_lo, vcc_lo, 9
	s_add_i32 s64, s64, vcc_lo
	s_mov_b32 s42, 0xbfb8aa3b
	s_mov_b32 s43, 1.0
	s_add_u32 s98, s26, 0xb000000
	s_addc_u32 s99, s27, 0
	s_add_u32 s98, s98, s64
	s_addc_u32 s99, s99, 0
	v_pk_mul_f32 v[128:129], v[124:125], s[42:43] op_sel_hi:[1,0]
	v_pk_mul_f32 v[130:131], v[126:127], s[42:43] op_sel_hi:[1,0]
	v_pk_mul_f32 v[132:133], v[120:121], s[42:43] op_sel_hi:[1,0]
	v_pk_mul_f32 v[134:135], v[122:123], s[42:43] op_sel_hi:[1,0]
	v_pk_mul_f32 v[136:137], v[112:113], s[42:43] op_sel_hi:[1,0]
	v_pk_mul_f32 v[138:139], v[114:115], s[42:43] op_sel_hi:[1,0]
	v_exp_f32_e32 v128, v128
	v_exp_f32_e32 v129, v129
	v_exp_f32_e32 v130, v130
	v_exp_f32_e32 v131, v131
	v_exp_f32_e32 v132, v132
	v_exp_f32_e32 v133, v133
	v_exp_f32_e32 v134, v134
	v_exp_f32_e32 v135, v135
	v_exp_f32_e32 v136, v136
	v_exp_f32_e32 v137, v137
	v_exp_f32_e32 v138, v138
	v_exp_f32_e32 v139, v139
	v_pk_add_f32 v[128:129], v[128:129], s[42:43] op_sel:[0,1] op_sel_hi:[1,1]
	v_pk_add_f32 v[130:131], v[130:131], s[42:43] op_sel:[0,1] op_sel_hi:[1,1]
	v_pk_add_f32 v[132:133], v[132:133], s[42:43] op_sel:[0,1] op_sel_hi:[1,1]
	v_pk_add_f32 v[134:135], v[134:135], s[42:43] op_sel:[0,1] op_sel_hi:[1,1]
	v_pk_add_f32 v[136:137], v[136:137], s[42:43] op_sel:[0,1] op_sel_hi:[1,1]
	v_pk_add_f32 v[138:139], v[138:139], s[42:43] op_sel:[0,1] op_sel_hi:[1,1]
	v_rcp_f32_e32 v128, v128
	v_rcp_f32_e32 v129, v129
	v_rcp_f32_e32 v130, v130
	v_rcp_f32_e32 v131, v131
	v_rcp_f32_e32 v132, v132
	v_rcp_f32_e32 v133, v133
	v_rcp_f32_e32 v134, v134
	v_rcp_f32_e32 v135, v135
	v_rcp_f32_e32 v136, v136
	v_rcp_f32_e32 v137, v137
	v_rcp_f32_e32 v138, v138
	v_rcp_f32_e32 v139, v139
	v_pk_mul_f32 v[128:129], v[116:117], v[128:129]
	v_pk_mul_f32 v[130:131], v[118:119], v[130:131]
	v_pk_mul_f32 v[132:133], v[120:121], v[132:133]
	v_pk_mul_f32 v[134:135], v[122:123], v[134:135]
	v_pk_mul_f32 v[136:137], v[112:113], v[136:137]
	v_pk_mul_f32 v[138:139], v[114:115], v[138:139]
	v_cvt_pk_bf16_f32 v198, v128, v129
	v_cvt_pk_bf16_f32 v199, v130, v131
	v_cvt_pk_bf16_f32 v206, v132, v133
	v_cvt_pk_bf16_f32 v207, v134, v135
	v_cvt_pk_bf16_f32 v214, v136, v137
	v_cvt_pk_bf16_f32 v215, v138, v139
	global_store_dwordx2 v243, v[214:215], s[98:99] nt
	s_add_u32 s98, s98, 0x800
	s_addc_u32 s99, s99, 0
	v_pk_mul_f32 v[128:129], v[108:109], s[42:43] op_sel_hi:[1,0]
	v_pk_mul_f32 v[130:131], v[110:111], s[42:43] op_sel_hi:[1,0]
	v_pk_mul_f32 v[132:133], v[104:105], s[42:43] op_sel_hi:[1,0]
	v_pk_mul_f32 v[134:135], v[106:107], s[42:43] op_sel_hi:[1,0]
	v_pk_mul_f32 v[136:137], v[80:81], s[42:43] op_sel_hi:[1,0]
	v_pk_mul_f32 v[138:139], v[82:83], s[42:43] op_sel_hi:[1,0]
	v_exp_f32_e32 v128, v128
	v_exp_f32_e32 v129, v129
	v_exp_f32_e32 v130, v130
	v_exp_f32_e32 v131, v131
	v_exp_f32_e32 v132, v132
; __device__ __forceinline__ float sigmoidf_(float x) { return __builtin_amdgcn_rcpf(1.0f + __builtin_amdgcn_exp2f(-1.44269504089f * x)); }
; __device__ __forceinline__ float siluf_(float x) { return x * sigmoidf_(x); }
; __device__ __forceinline__ u32x2 pk4(f32x4 v) { u32x2 r; r.x = pk_bf16(v[0], v[1]); r.y = pk_bf16(v[2], v[3]); return r; }
; __device__ __forceinline__ int pf(int fq) { return (fq >> 1) | ((fq & 1) << 1); }
;     __device__ __forceinline__ void operator()(const f32x4 (&acc)[2][2][4][2], const Unit& u, int wr, int wc, int fr, int fq) const {
;     ...
;                 for (int ai = 0; ai < 2; ++ai) {
;                     u32x2 gv[4], zv[4];
; #pragma unroll
;                     for (int m = 0; m < 4; ++m) {
;                         const f32x4 Vv = acc[ai][0][m][0], Gv = acc[ai][0][m][1], Zb = acc[ai][1][m][0], Zx = acc[ai][1][m][1]; f32x4 o0, o1, o2;
; #pragma unroll
;                         for (int j = 0; j < 4; ++j) { o0[j] = Vv[j] * sigmoidf_(Gv[j]); o1[j] = siluf_(Zb[j]); o2[j] = siluf_(Zx[j]); }
;                         gv[m] = pk4(o0); zv[m] = pk4(o1);
;                         { const int c = (u.pn & 3) * 64 + wc * 16;
;                           __builtin_nontemporal_store(pk4(o2), (u32x2*)SZX + native_slot(u.pm, (u.pn & 15) >> 2, wr * 4 + ((c >> 5) & 3), ai, m, c >> 7, (c >> 4) & 1, pf(fq) * 16 + fr)); }
;                     }
	v_exp_f32_e32 v133, v133
	v_exp_f32_e32 v134, v134
	v_exp_f32_e32 v135, v135
	v_exp_f32_e32 v136, v136
	v_exp_f32_e32 v137, v137
	v_exp_f32_e32 v138, v138
	v_exp_f32_e32 v139, v139
	v_pk_add_f32 v[128:129], v[128:129], s[42:43] op_sel:[0,1] op_sel_hi:[1,1]
	v_pk_add_f32 v[130:131], v[130:131], s[42:43] op_sel:[0,1] op_sel_hi:[1,1]
	v_pk_add_f32 v[132:133], v[132:133], s[42:43] op_sel:[0,1] op_sel_hi:[1,1]
	v_pk_add_f32 v[134:135], v[134:135], s[42:43] op_sel:[0,1] op_sel_hi:[1,1]
	v_pk_add_f32 v[136:137], v[136:137], s[42:43] op_sel:[0,1] op_sel_hi:[1,1]
	v_pk_add_f32 v[138:139], v[138:139], s[42:43] op_sel:[0,1] op_sel_hi:[1,1]
	v_rcp_f32_e32 v128, v128
	v_rcp_f32_e32 v129, v129
	v_rcp_f32_e32 v130, v130
	v_rcp_f32_e32 v131, v131
	v_rcp_f32_e32 v132, v132
	v_rcp_f32_e32 v133, v133
	v_rcp_f32_e32 v134, v134
	v_rcp_f32_e32 v135, v135
	v_rcp_f32_e32 v136, v136
	v_rcp_f32_e32 v137, v137
	v_rcp_f32_e32 v138, v138
	v_rcp_f32_e32 v139, v139
	v_pk_mul_f32 v[128:129], v[84:85], v[128:129]
	v_pk_mul_f32 v[130:131], v[86:87], v[130:131]
	v_pk_mul_f32 v[132:133], v[104:105], v[132:133]
	v_pk_mul_f32 v[134:135], v[106:107], v[134:135]
	v_pk_mul_f32 v[136:137], v[80:81], v[136:137]
	v_pk_mul_f32 v[138:139], v[82:83], v[138:139]
	v_cvt_pk_bf16_f32 v200, v128, v129
	v_cvt_pk_bf16_f32 v201, v130, v131
	v_cvt_pk_bf16_f32 v208, v132, v133
	v_cvt_pk_bf16_f32 v209, v134, v135
	v_cvt_pk_bf16_f32 v216, v136, v137
	v_cvt_pk_bf16_f32 v217, v138, v139
	global_store_dwordx2 v243, v[216:217], s[98:99] nt
	s_add_u32 s98, s98, 0x800
	s_addc_u32 s99, s99, 0
	v_pk_mul_f32 v[128:129], v[100:101], s[42:43] op_sel_hi:[1,0]
	v_pk_mul_f32 v[130:131], v[102:103], s[42:43] op_sel_hi:[1,0]
	v_pk_mul_f32 v[132:133], v[96:97], s[42:43] op_sel_hi:[1,0]
	v_pk_mul_f32 v[134:135], v[98:99], s[42:43] op_sel_hi:[1,0]
	v_pk_mul_f32 v[136:137], v[72:73], s[42:43] op_sel_hi:[1,0]
	v_pk_mul_f32 v[138:139], v[74:75], s[42:43] op_sel_hi:[1,0]
	v_exp_f32_e32 v128, v128
	v_exp_f32_e32 v129, v129
	v_exp_f32_e32 v130, v130
	v_exp_f32_e32 v131, v131
	v_exp_f32_e32 v132, v132
	v_exp_f32_e32 v133, v133
	v_exp_f32_e32 v134, v134
	v_exp_f32_e32 v135, v135
	v_exp_f32_e32 v136, v136
	v_exp_f32_e32 v137, v137
	v_exp_f32_e32 v138, v138
	v_exp_f32_e32 v139, v139
	v_pk_add_f32 v[128:129], v[128:129], s[42:43] op_sel:[0,1] op_sel_hi:[1,1]
	v_pk_add_f32 v[130:131], v[130:131], s[42:43] op_sel:[0,1] op_sel_hi:[1,1]
	v_pk_add_f32 v[132:133], v[132:133], s[42:43] op_sel:[0,1] op_sel_hi:[1,1]
	v_pk_add_f32 v[134:135], v[134:135], s[42:43] op_sel:[0,1] op_sel_hi:[1,1]
	v_pk_add_f32 v[136:137], v[136:137], s[42:43] op_sel:[0,1] op_sel_hi:[1,1]
	v_pk_add_f32 v[138:139], v[138:139], s[42:43] op_sel:[0,1] op_sel_hi:[1,1]
	v_rcp_f32_e32 v128, v128
	v_rcp_f32_e32 v129, v129
	v_rcp_f32_e32 v130, v130
	v_rcp_f32_e32 v131, v131
	v_rcp_f32_e32 v132, v132
	v_rcp_f32_e32 v133, v133
	v_rcp_f32_e32 v134, v134
	v_rcp_f32_e32 v135, v135
	v_rcp_f32_e32 v136, v136
	v_rcp_f32_e32 v137, v137
	v_rcp_f32_e32 v138, v138
	v_rcp_f32_e32 v139, v139
	v_pk_mul_f32 v[128:129], v[76:77], v[128:129]
	v_pk_mul_f32 v[130:131], v[78:79], v[130:131]
	v_pk_mul_f32 v[132:133], v[96:97], v[132:133]
	v_pk_mul_f32 v[134:135], v[98:99], v[134:135]
	v_pk_mul_f32 v[136:137], v[72:73], v[136:137]
	v_pk_mul_f32 v[138:139], v[74:75], v[138:139]
	v_cvt_pk_bf16_f32 v202, v128, v129
	v_cvt_pk_bf16_f32 v203, v130, v131
	v_cvt_pk_bf16_f32 v210, v132, v133
	v_cvt_pk_bf16_f32 v211, v134, v135
	v_cvt_pk_bf16_f32 v214, v136, v137
	v_cvt_pk_bf16_f32 v215, v138, v139
	global_store_dwordx2 v243, v[214:215], s[98:99] nt
	s_add_u32 s98, s98, 0x800
	s_addc_u32 s99, s99, 0
	v_pk_mul_f32 v[128:129], v[92:93], s[42:43] op_sel_hi:[1,0]
	v_pk_mul_f32 v[130:131], v[94:95], s[42:43] op_sel_hi:[1,0]
	v_pk_mul_f32 v[132:133], v[88:89], s[42:43] op_sel_hi:[1,0]
	v_pk_mul_f32 v[134:135], v[90:91], s[42:43] op_sel_hi:[1,0]
	v_pk_mul_f32 v[136:137], v[64:65], s[42:43] op_sel_hi:[1,0]
	v_pk_mul_f32 v[138:139], v[66:67], s[42:43] op_sel_hi:[1,0]
	v_exp_f32_e32 v128, v128
	v_exp_f32_e32 v129, v129
	v_exp_f32_e32 v130, v130
	v_exp_f32_e32 v131, v131
	v_exp_f32_e32 v132, v132
	v_exp_f32_e32 v133, v133
	v_exp_f32_e32 v134, v134
	v_exp_f32_e32 v135, v135
	v_exp_f32_e32 v136, v136
	v_exp_f32_e32 v137, v137
	v_exp_f32_e32 v138, v138
	v_exp_f32_e32 v139, v139
	v_pk_add_f32 v[128:129], v[128:129], s[42:43] op_sel:[0,1] op_sel_hi:[1,1]
	v_pk_add_f32 v[130:131], v[130:131], s[42:43] op_sel:[0,1] op_sel_hi:[1,1]
	v_pk_add_f32 v[132:133], v[132:133], s[42:43] op_sel:[0,1] op_sel_hi:[1,1]
	v_pk_add_f32 v[134:135], v[134:135], s[42:43] op_sel:[0,1] op_sel_hi:[1,1]
	v_pk_add_f32 v[136:137], v[136:137], s[42:43] op_sel:[0,1] op_sel_hi:[1,1]
	v_pk_add_f32 v[138:139], v[138:139], s[42:43] op_sel:[0,1] op_sel_hi:[1,1]
	v_rcp_f32_e32 v128, v128
	v_rcp_f32_e32 v129, v129
	v_rcp_f32_e32 v130, v130
	v_rcp_f32_e32 v131, v131
	v_rcp_f32_e32 v132, v132
	v_rcp_f32_e32 v133, v133
	v_rcp_f32_e32 v134, v134
	v_rcp_f32_e32 v135, v135
	v_rcp_f32_e32 v136, v136
	v_rcp_f32_e32 v137, v137
	v_rcp_f32_e32 v138, v138
	v_rcp_f32_e32 v139, v139
	v_pk_mul_f32 v[128:129], v[68:69], v[128:129]
	v_pk_mul_f32 v[130:131], v[70:71], v[130:131]
	v_pk_mul_f32 v[132:133], v[88:89], v[132:133]
	v_pk_mul_f32 v[134:135], v[90:91], v[134:135]
	v_pk_mul_f32 v[136:137], v[64:65], v[136:137]
	v_pk_mul_f32 v[138:139], v[66:67], v[138:139]
	v_cvt_pk_bf16_f32 v204, v128, v129
	v_cvt_pk_bf16_f32 v205, v130, v131
	v_cvt_pk_bf16_f32 v212, v132, v133
	v_cvt_pk_bf16_f32 v213, v134, v135
	v_cvt_pk_bf16_f32 v216, v136, v137
	v_cvt_pk_bf16_f32 v217, v138, v139
	global_store_dwordx2 v243, v[216:217], s[98:99] nt
	s_add_u32 s98, s98, 0x800
; __device__ __forceinline__ float sigmoidf_(float x) { return __builtin_amdgcn_rcpf(1.0f + __builtin_amdgcn_exp2f(-1.44269504089f * x)); }
; __device__ __forceinline__ float siluf_(float x) { return x * sigmoidf_(x); }
; __device__ __forceinline__ u32x2 pk4(f32x4 v) { u32x2 r; r.x = pk_bf16(v[0], v[1]); r.y = pk_bf16(v[2], v[3]); return r; }
; __device__ __forceinline__ int pf(int fq) { return (fq >> 1) | ((fq & 1) << 1); }
;     __device__ __forceinline__ void operator()(const f32x4 (&acc)[2][2][4][2], const Unit& u, int wr, int wc, int fr, int fq) const {
;     ...
;                 for (int ai = 0; ai < 2; ++ai) {
;                     u32x2 gv[4], zv[4];
; #pragma unroll
;                     for (int m = 0; m < 4; ++m) {
;                         const f32x4 Vv = acc[ai][0][m][0], Gv = acc[ai][0][m][1], Zb = acc[ai][1][m][0], Zx = acc[ai][1][m][1]; f32x4 o0, o1, o2;
; #pragma unroll
;                         for (int j = 0; j < 4; ++j) { o0[j] = Vv[j] * sigmoidf_(Gv[j]); o1[j] = siluf_(Zb[j]); o2[j] = siluf_(Zx[j]); }
;                         gv[m] = pk4(o0); zv[m] = pk4(o1);
;                         { const int c = (u.pn & 3) * 64 + wc * 16;
;                           __builtin_nontemporal_store(pk4(o2), (u32x2*)SZX + native_slot(u.pm, (u.pn & 15) >> 2, wr * 4 + ((c >> 5) & 3), ai, m, c >> 7, (c >> 4) & 1, pf(fq) * 16 + fr)); }
;                     }
; #pragma unroll
;                     for (int pr = 0; pr < 2; ++pr) {
;                         store_pair16(GLU + (size_t)(rowb + ai * 128 + pr * 32) * 1024 + chw, gv[2 * pr], gv[2 * pr + 1], fq);
;                         store_pair16(SZB + (size_t)(rowb + ai * 128 + pr * 32) * 1024 + chw, zv[2 * pr], zv[2 * pr + 1], fq);
;                     }
	s_addc_u32 s99, s99, 0
	s_nop 1
	v_permlane32_swap_b32_e32 v198, v200
	v_permlane32_swap_b32_e32 v199, v201
	v_lshl_add_u64 v[248:249], s[14:15], 0, v[246:247]
	global_store_dwordx4 v[248:249], v[198:201], off
	s_nop 1
	v_permlane32_swap_b32_e32 v206, v208
	v_permlane32_swap_b32_e32 v207, v209
	v_lshl_add_u64 v[248:249], s[52:53], 0, v[246:247]
	global_store_dwordx4 v[248:249], v[206:209], off
	s_nop 1
	v_permlane32_swap_b32_e32 v202, v204
	v_permlane32_swap_b32_e32 v203, v205
	s_mov_b64 s[4:5], 0x10000
	v_lshl_add_u64 v[248:249], v[246:247], 0, s[4:5]
	v_lshl_add_u64 v[248:249], s[14:15], 0, v[248:249]
	global_store_dwordx4 v[248:249], v[202:205], off
	s_nop 1
	v_permlane32_swap_b32_e32 v210, v212
	v_permlane32_swap_b32_e32 v211, v213
	s_mov_b64 s[4:5], 0x10000
	v_lshl_add_u64 v[248:249], v[246:247], 0, s[4:5]
	v_lshl_add_u64 v[248:249], s[52:53], 0, v[248:249]
	global_store_dwordx4 v[248:249], v[210:213], off
	v_pk_mul_f32 v[128:129], v[60:61], s[42:43] op_sel_hi:[1,0]
	v_pk_mul_f32 v[130:131], v[62:63], s[42:43] op_sel_hi:[1,0]
	v_pk_mul_f32 v[132:133], v[56:57], s[42:43] op_sel_hi:[1,0]
	v_pk_mul_f32 v[134:135], v[58:59], s[42:43] op_sel_hi:[1,0]
	v_pk_mul_f32 v[136:137], v[48:49], s[42:43] op_sel_hi:[1,0]
	v_pk_mul_f32 v[138:139], v[50:51], s[42:43] op_sel_hi:[1,0]
	v_exp_f32_e32 v128, v128
	v_exp_f32_e32 v129, v129
	v_exp_f32_e32 v130, v130
	v_exp_f32_e32 v131, v131
	v_exp_f32_e32 v132, v132
	v_exp_f32_e32 v133, v133
	v_exp_f32_e32 v134, v134
	v_exp_f32_e32 v135, v135
	v_exp_f32_e32 v136, v136
	v_exp_f32_e32 v137, v137
	v_exp_f32_e32 v138, v138
	v_exp_f32_e32 v139, v139
	v_pk_add_f32 v[128:129], v[128:129], s[42:43] op_sel:[0,1] op_sel_hi:[1,1]
	v_pk_add_f32 v[130:131], v[130:131], s[42:43] op_sel:[0,1] op_sel_hi:[1,1]
	v_pk_add_f32 v[132:133], v[132:133], s[42:43] op_sel:[0,1] op_sel_hi:[1,1]
	v_pk_add_f32 v[134:135], v[134:135], s[42:43] op_sel:[0,1] op_sel_hi:[1,1]
	v_pk_add_f32 v[136:137], v[136:137], s[42:43] op_sel:[0,1] op_sel_hi:[1,1]
	v_pk_add_f32 v[138:139], v[138:139], s[42:43] op_sel:[0,1] op_sel_hi:[1,1]
	v_rcp_f32_e32 v128, v128
	v_rcp_f32_e32 v129, v129
	v_rcp_f32_e32 v130, v130
	v_rcp_f32_e32 v131, v131
	v_rcp_f32_e32 v132, v132
	v_rcp_f32_e32 v133, v133
	v_rcp_f32_e32 v134, v134
	v_rcp_f32_e32 v135, v135
	v_rcp_f32_e32 v136, v136
	v_rcp_f32_e32 v137, v137
	v_rcp_f32_e32 v138, v138
	v_rcp_f32_e32 v139, v139
	v_pk_mul_f32 v[128:129], v[52:53], v[128:129]
	v_pk_mul_f32 v[130:131], v[54:55], v[130:131]
	v_pk_mul_f32 v[132:133], v[56:57], v[132:133]
	v_pk_mul_f32 v[134:135], v[58:59], v[134:135]
	v_pk_mul_f32 v[136:137], v[48:49], v[136:137]
	v_pk_mul_f32 v[138:139], v[50:51], v[138:139]
	v_cvt_pk_bf16_f32 v198, v128, v129
	v_cvt_pk_bf16_f32 v199, v130, v131
	v_cvt_pk_bf16_f32 v206, v132, v133
	v_cvt_pk_bf16_f32 v207, v134, v135
	v_cvt_pk_bf16_f32 v214, v136, v137
	v_cvt_pk_bf16_f32 v215, v138, v139
	global_store_dwordx2 v243, v[214:215], s[98:99] nt
	s_add_u32 s98, s98, 0x800
	s_addc_u32 s99, s99, 0
	v_pk_mul_f32 v[128:129], v[44:45], s[42:43] op_sel_hi:[1,0]
	v_pk_mul_f32 v[130:131], v[46:47], s[42:43] op_sel_hi:[1,0]
	v_pk_mul_f32 v[132:133], v[40:41], s[42:43] op_sel_hi:[1,0]
	v_pk_mul_f32 v[134:135], v[42:43], s[42:43] op_sel_hi:[1,0]
	v_pk_mul_f32 v[136:137], v[16:17], s[42:43] op_sel_hi:[1,0]
	v_pk_mul_f32 v[138:139], v[18:19], s[42:43] op_sel_hi:[1,0]
	v_exp_f32_e32 v128, v128
	v_exp_f32_e32 v129, v129
	v_exp_f32_e32 v130, v130
	v_exp_f32_e32 v131, v131
	v_exp_f32_e32 v132, v132
	v_exp_f32_e32 v133, v133
	v_exp_f32_e32 v134, v134
	v_exp_f32_e32 v135, v135
	v_exp_f32_e32 v136, v136
	v_exp_f32_e32 v137, v137
	v_exp_f32_e32 v138, v138
	v_exp_f32_e32 v139, v139
	v_pk_add_f32 v[128:129], v[128:129], s[42:43] op_sel:[0,1] op_sel_hi:[1,1]
	v_pk_add_f32 v[130:131], v[130:131], s[42:43] op_sel:[0,1] op_sel_hi:[1,1]
	v_pk_add_f32 v[132:133], v[132:133], s[42:43] op_sel:[0,1] op_sel_hi:[1,1]
	v_pk_add_f32 v[134:135], v[134:135], s[42:43] op_sel:[0,1] op_sel_hi:[1,1]
	v_pk_add_f32 v[136:137], v[136:137], s[42:43] op_sel:[0,1] op_sel_hi:[1,1]
	v_pk_add_f32 v[138:139], v[138:139], s[42:43] op_sel:[0,1] op_sel_hi:[1,1]
	v_rcp_f32_e32 v128, v128
	v_rcp_f32_e32 v129, v129
	v_rcp_f32_e32 v130, v130
	v_rcp_f32_e32 v131, v131
	v_rcp_f32_e32 v132, v132
	v_rcp_f32_e32 v133, v133
	v_rcp_f32_e32 v134, v134
	v_rcp_f32_e32 v135, v135
	v_rcp_f32_e32 v136, v136
	v_rcp_f32_e32 v137, v137
	v_rcp_f32_e32 v138, v138
	v_rcp_f32_e32 v139, v139
	v_pk_mul_f32 v[128:129], v[20:21], v[128:129]
	v_pk_mul_f32 v[130:131], v[22:23], v[130:131]
	v_pk_mul_f32 v[132:133], v[40:41], v[132:133]
	v_pk_mul_f32 v[134:135], v[42:43], v[134:135]
	v_pk_mul_f32 v[136:137], v[16:17], v[136:137]
	v_pk_mul_f32 v[138:139], v[18:19], v[138:139]
	v_cvt_pk_bf16_f32 v200, v128, v129
	v_cvt_pk_bf16_f32 v201, v130, v131
	v_cvt_pk_bf16_f32 v208, v132, v133
	v_cvt_pk_bf16_f32 v209, v134, v135
	v_cvt_pk_bf16_f32 v216, v136, v137
	v_cvt_pk_bf16_f32 v217, v138, v139
	global_store_dwordx2 v243, v[216:217], s[98:99] nt
	s_add_u32 s98, s98, 0x800
	s_addc_u32 s99, s99, 0
	v_pk_mul_f32 v[128:129], v[36:37], s[42:43] op_sel_hi:[1,0]
	v_pk_mul_f32 v[130:131], v[38:39], s[42:43] op_sel_hi:[1,0]
	v_pk_mul_f32 v[132:133], v[32:33], s[42:43] op_sel_hi:[1,0]
	v_pk_mul_f32 v[134:135], v[34:35], s[42:43] op_sel_hi:[1,0]
; __device__ __forceinline__ float sigmoidf_(float x) { return __builtin_amdgcn_rcpf(1.0f + __builtin_amdgcn_exp2f(-1.44269504089f * x)); }
; __device__ __forceinline__ float siluf_(float x) { return x * sigmoidf_(x); }
; __device__ __forceinline__ u32x2 pk4(f32x4 v) { u32x2 r; r.x = pk_bf16(v[0], v[1]); r.y = pk_bf16(v[2], v[3]); return r; }
; __device__ __forceinline__ int pf(int fq) { return (fq >> 1) | ((fq & 1) << 1); }
;     __device__ __forceinline__ void operator()(const f32x4 (&acc)[2][2][4][2], const Unit& u, int wr, int wc, int fr, int fq) const {
;     ...
;                 for (int ai = 0; ai < 2; ++ai) {
;                     u32x2 gv[4], zv[4];
; #pragma unroll
;                     for (int m = 0; m < 4; ++m) {
;                         const f32x4 Vv = acc[ai][0][m][0], Gv = acc[ai][0][m][1], Zb = acc[ai][1][m][0], Zx = acc[ai][1][m][1]; f32x4 o0, o1, o2;
; #pragma unroll
;                         for (int j = 0; j < 4; ++j) { o0[j] = Vv[j] * sigmoidf_(Gv[j]); o1[j] = siluf_(Zb[j]); o2[j] = siluf_(Zx[j]); }
;                         gv[m] = pk4(o0); zv[m] = pk4(o1);
;                         { const int c = (u.pn & 3) * 64 + wc * 16;
;                           __builtin_nontemporal_store(pk4(o2), (u32x2*)SZX + native_slot(u.pm, (u.pn & 15) >> 2, wr * 4 + ((c >> 5) & 3), ai, m, c >> 7, (c >> 4) & 1, pf(fq) * 16 + fr)); }
;                     }
; #pragma unroll
;                     for (int pr = 0; pr < 2; ++pr) {
;                         store_pair16(GLU + (size_t)(rowb + ai * 128 + pr * 32) * 1024 + chw, gv[2 * pr], gv[2 * pr + 1], fq);
;                         store_pair16(SZB + (size_t)(rowb + ai * 128 + pr * 32) * 1024 + chw, zv[2 * pr], zv[2 * pr + 1], fq);
;                     }
	v_pk_mul_f32 v[136:137], v[8:9], s[42:43] op_sel_hi:[1,0]
	v_pk_mul_f32 v[138:139], v[10:11], s[42:43] op_sel_hi:[1,0]
	v_exp_f32_e32 v128, v128
	v_exp_f32_e32 v129, v129
	v_exp_f32_e32 v130, v130
	v_exp_f32_e32 v131, v131
	v_exp_f32_e32 v132, v132
	v_exp_f32_e32 v133, v133
	v_exp_f32_e32 v134, v134
	v_exp_f32_e32 v135, v135
	v_exp_f32_e32 v136, v136
	v_exp_f32_e32 v137, v137
	v_exp_f32_e32 v138, v138
	v_exp_f32_e32 v139, v139
	v_pk_add_f32 v[128:129], v[128:129], s[42:43] op_sel:[0,1] op_sel_hi:[1,1]
	v_pk_add_f32 v[130:131], v[130:131], s[42:43] op_sel:[0,1] op_sel_hi:[1,1]
	v_pk_add_f32 v[132:133], v[132:133], s[42:43] op_sel:[0,1] op_sel_hi:[1,1]
	v_pk_add_f32 v[134:135], v[134:135], s[42:43] op_sel:[0,1] op_sel_hi:[1,1]
	v_pk_add_f32 v[136:137], v[136:137], s[42:43] op_sel:[0,1] op_sel_hi:[1,1]
	v_pk_add_f32 v[138:139], v[138:139], s[42:43] op_sel:[0,1] op_sel_hi:[1,1]
	v_rcp_f32_e32 v128, v128
	v_rcp_f32_e32 v129, v129
	v_rcp_f32_e32 v130, v130
	v_rcp_f32_e32 v131, v131
	v_rcp_f32_e32 v132, v132
	v_rcp_f32_e32 v133, v133
	v_rcp_f32_e32 v134, v134
	v_rcp_f32_e32 v135, v135
	v_rcp_f32_e32 v136, v136
	v_rcp_f32_e32 v137, v137
	v_rcp_f32_e32 v138, v138
	v_rcp_f32_e32 v139, v139
	v_pk_mul_f32 v[128:129], v[12:13], v[128:129]
	v_pk_mul_f32 v[130:131], v[14:15], v[130:131]
	v_pk_mul_f32 v[132:133], v[32:33], v[132:133]
	v_pk_mul_f32 v[134:135], v[34:35], v[134:135]
	v_pk_mul_f32 v[136:137], v[8:9], v[136:137]
	v_pk_mul_f32 v[138:139], v[10:11], v[138:139]
	v_cvt_pk_bf16_f32 v202, v128, v129
	v_cvt_pk_bf16_f32 v203, v130, v131
	v_cvt_pk_bf16_f32 v210, v132, v133
	v_cvt_pk_bf16_f32 v211, v134, v135
	v_cvt_pk_bf16_f32 v214, v136, v137
	v_cvt_pk_bf16_f32 v215, v138, v139
	global_store_dwordx2 v243, v[214:215], s[98:99] nt
	s_add_u32 s98, s98, 0x800
	s_addc_u32 s99, s99, 0
	v_pk_mul_f32 v[128:129], v[28:29], s[42:43] op_sel_hi:[1,0]
	v_pk_mul_f32 v[130:131], v[30:31], s[42:43] op_sel_hi:[1,0]
	v_pk_mul_f32 v[132:133], v[24:25], s[42:43] op_sel_hi:[1,0]
	v_pk_mul_f32 v[134:135], v[26:27], s[42:43] op_sel_hi:[1,0]
	v_pk_mul_f32 v[136:137], v[0:1], s[42:43] op_sel_hi:[1,0]
	v_pk_mul_f32 v[138:139], v[2:3], s[42:43] op_sel_hi:[1,0]
	v_exp_f32_e32 v128, v128
	v_exp_f32_e32 v129, v129
	v_exp_f32_e32 v130, v130
	v_exp_f32_e32 v131, v131
	v_exp_f32_e32 v132, v132
	v_exp_f32_e32 v133, v133
	v_exp_f32_e32 v134, v134
	v_exp_f32_e32 v135, v135
	v_exp_f32_e32 v136, v136
	v_exp_f32_e32 v137, v137
	v_exp_f32_e32 v138, v138
	v_exp_f32_e32 v139, v139
	v_pk_add_f32 v[128:129], v[128:129], s[42:43] op_sel:[0,1] op_sel_hi:[1,1]
	v_pk_add_f32 v[130:131], v[130:131], s[42:43] op_sel:[0,1] op_sel_hi:[1,1]
	v_pk_add_f32 v[132:133], v[132:133], s[42:43] op_sel:[0,1] op_sel_hi:[1,1]
	v_pk_add_f32 v[134:135], v[134:135], s[42:43] op_sel:[0,1] op_sel_hi:[1,1]
	v_pk_add_f32 v[136:137], v[136:137], s[42:43] op_sel:[0,1] op_sel_hi:[1,1]
	v_pk_add_f32 v[138:139], v[138:139], s[42:43] op_sel:[0,1] op_sel_hi:[1,1]
	v_rcp_f32_e32 v128, v128
	v_rcp_f32_e32 v129, v129
	v_rcp_f32_e32 v130, v130
	v_rcp_f32_e32 v131, v131
	v_rcp_f32_e32 v132, v132
	v_rcp_f32_e32 v133, v133
	v_rcp_f32_e32 v134, v134
	v_rcp_f32_e32 v135, v135
	v_rcp_f32_e32 v136, v136
	v_rcp_f32_e32 v137, v137
	v_rcp_f32_e32 v138, v138
	v_rcp_f32_e32 v139, v139
	v_pk_mul_f32 v[128:129], v[4:5], v[128:129]
	v_pk_mul_f32 v[130:131], v[6:7], v[130:131]
	v_pk_mul_f32 v[132:133], v[24:25], v[132:133]
	v_pk_mul_f32 v[134:135], v[26:27], v[134:135]
	v_pk_mul_f32 v[136:137], v[0:1], v[136:137]
	v_pk_mul_f32 v[138:139], v[2:3], v[138:139]
	v_cvt_pk_bf16_f32 v204, v128, v129
	v_cvt_pk_bf16_f32 v205, v130, v131
	v_cvt_pk_bf16_f32 v212, v132, v133
	v_cvt_pk_bf16_f32 v213, v134, v135
	v_cvt_pk_bf16_f32 v216, v136, v137
	v_cvt_pk_bf16_f32 v217, v138, v139
	global_store_dwordx2 v243, v[216:217], s[98:99] nt
	s_add_u32 s98, s98, 0x800
	s_addc_u32 s99, s99, 0
	s_nop 1
	v_permlane32_swap_b32_e32 v198, v200
	v_permlane32_swap_b32_e32 v199, v201
	s_mov_b64 s[4:5], 0x40000
	v_lshl_add_u64 v[248:249], v[246:247], 0, s[4:5]
	v_lshl_add_u64 v[248:249], s[14:15], 0, v[248:249]
	global_store_dwordx4 v[248:249], v[198:201], off
	s_nop 1
	v_permlane32_swap_b32_e32 v206, v208
	v_permlane32_swap_b32_e32 v207, v209
	s_mov_b64 s[4:5], 0x40000
	v_lshl_add_u64 v[248:249], v[246:247], 0, s[4:5]
	v_lshl_add_u64 v[248:249], s[52:53], 0, v[248:249]
	global_store_dwordx4 v[248:249], v[206:209], off
	s_nop 1
	v_permlane32_swap_b32_e32 v202, v204
	v_permlane32_swap_b32_e32 v203, v205
	s_mov_b64 s[4:5], 0x50000
	v_lshl_add_u64 v[248:249], v[246:247], 0, s[4:5]
	v_lshl_add_u64 v[248:249], s[14:15], 0, v[248:249]
	global_store_dwordx4 v[248:249], v[202:205], off
	s_nop 1
	v_permlane32_swap_b32_e32 v210, v212
	v_permlane32_swap_b32_e32 v211, v213
	s_mov_b64 s[4:5], 0x50000
	v_lshl_add_u64 v[248:249], v[246:247], 0, s[4:5]
	v_lshl_add_u64 v[248:249], s[52:53], 0, v[248:249]
	global_store_dwordx4 v[248:249], v[210:213], off
	s_branch .LBB0_287
.Lp1e_k0:
	s_lshl_b32 s81, s90, 6
	s_and_b32 s4, s81, 0x3c0
	s_or_b32 s35, s4, s78
	v_lshl_add_u32 v174, s96, 8, v146
	s_mov_b64 s[42:43], -1
	s_mov_b64 s[4:5], 0
	s_cmp_lt_i32 s13, 1
	s_mov_b64 s[30:31], 0
	s_cbranch_scc1 .LBB0_273
	s_cmp_eq_u32 s13, 1
	s_mov_b64 s[30:31], -1
	s_cbranch_scc0 .LBB0_272
.LBB0_272:
	s_mov_b64 s[42:43], 0

; __device__ __forceinline__ float siluf_(float x) { return x * sigmoidf_(x); }
; __device__ __forceinline__ u32x2 pk4(f32x4 v) { u32x2 r; r.x = pk_bf16(v[0], v[1]); r.y = pk_bf16(v[2], v[3]); return r; }
; template <int CTRL> __device__ __forceinline__ float dppf(float old, float v) { return __int_as_float(__builtin_amdgcn_update_dpp(__float_as_int(old), __float_as_int(v), CTRL, 0xf, 0xf, false)); }
;     __device__ __forceinline__ void operator()(const f32x4 (&acc)[2][2][4][2], const Unit& u, int wr, int wc, int fr, int fq) const {
;     ...
;             if (u.kind == 0) {
;                 const f32x4 w0 = *(const f32x4*)(convw + ch), w1 = *(const f32x4*)(convw + 1024 + ch), w2 = *(const f32x4*)(convw + 2048 + ch);
; #pragma unroll
;                 for (int ai = 0; ai < 2; ++ai) {
;                     const int blk = u.pm * 4 + ai * 2 + wr;
;                     f32x4 pprev = (f32x4){0.f, 0.f, 0.f, 0.f}; u32x2 hv[4];
; #pragma unroll
;                     for (int m = 0; m < 4; ++m) {
;                         const f32x4 Bv = acc[ai][0][m][0], Cv = acc[ai][0][m][1], Xv = acc[ai][1][m][0], Zv = acc[ai][1][m][1];
;                         const f32x4 p = Cv * Xv; f32x4 ga, p1, p2;
; #pragma unroll
;                         for (int j = 0; j < 4; ++j) {
;                             ga[j] = siluf_(Zv[j]) * Bv[j];
;                             const float r1 = (m > 0) ? dppf<0x121>(0.f, pprev[j]) : 0.f, r2 = (m > 0) ? dppf<0x122>(0.f, pprev[j]) : 0.f;
;                             p1[j] = dppf<0x111>(r1, p[j]); p2[j] = dppf<0x112>(r2, p[j]);
;                         }
;                         const f32x4 cv = w2 * p + w1 * p1 + w0 * p2;
;                         hv[m] = pk4(ga * cv);
;                         if (m == 3 && fr >= 14) *(u32x2*)(PAT + (size_t)(blk * 2 + (fr - 14)) * 1024 + ch) = pk4(p);
;                         if (m == 0 && fr < 2) *(u32x2*)(GAH + (size_t)(blk * 2 + fr) * 1024 + ch) = pk4(ga);
;                         pprev = p;
;                     }
.LBB0_275:
	v_mul_f32_e32 v128, 0xbfb8aa3b, v112
	v_mul_f32_e32 v129, 0xbfb8aa3b, v113
	v_mul_f32_e32 v130, 0xbfb8aa3b, v114
	v_mul_f32_e32 v131, 0xbfb8aa3b, v115
	v_mul_f32_e32 v132, 0xbfb8aa3b, v80
	v_mul_f32_e32 v133, 0xbfb8aa3b, v81
	v_mul_f32_e32 v134, 0xbfb8aa3b, v82
	v_mul_f32_e32 v135, 0xbfb8aa3b, v83
	v_mul_f32_e32 v136, 0xbfb8aa3b, v72
	v_mul_f32_e32 v137, 0xbfb8aa3b, v73
	v_mul_f32_e32 v138, 0xbfb8aa3b, v74
	v_mul_f32_e32 v139, 0xbfb8aa3b, v75
	v_mul_f32_e32 v144, 0xbfb8aa3b, v64
	v_mul_f32_e32 v165, 0xbfb8aa3b, v65
	v_mul_f32_e32 v175, 0xbfb8aa3b, v66
	v_mul_f32_e32 v176, 0xbfb8aa3b, v67
	v_exp_f32_e32 v183, v128
	v_exp_f32_e32 v182, v129
	v_exp_f32_e32 v181, v130
	v_exp_f32_e32 v180, v131
	v_exp_f32_e32 v212, v132
	v_exp_f32_e32 v211, v133
	v_exp_f32_e32 v210, v134
	v_exp_f32_e32 v209, v135
	v_exp_f32_e32 v208, v136
	v_exp_f32_e32 v207, v137
	v_exp_f32_e32 v206, v138
	v_exp_f32_e32 v205, v139
	v_exp_f32_e32 v204, v144
	v_exp_f32_e32 v203, v165
	v_exp_f32_e32 v202, v175
	v_exp_f32_e32 v201, v176
	s_andn2_b64 vcc, exec, s[30:31]
	v_ashrrev_i32_e32 v175, 31, v174
	v_lshlrev_b32_e32 v144, 1, v164
	v_lshlrev_b32_e32 v176, 1, v166
	v_or_b32_e32 v178, 32, v174
	v_mul_f32_e32 v200, 0xbfb8aa3b, v48
	v_mul_f32_e32 v199, 0xbfb8aa3b, v49
	v_mul_f32_e32 v198, 0xbfb8aa3b, v50
	s_cbranch_vccnz .LBB0_277
.LBB0_277:
	s_andn2_b64 vcc, exec, s[4:5]
	s_cbranch_vccnz .LBB0_287
	v_or_b32_e32 v165, s35, v194
	v_readlane_b32 s4, v255, 27
	v_lshlrev_b32_e32 v132, 2, v165
	v_readlane_b32 s5, v255, 28
	global_load_dwordx4 v[128:131], v132, s[44:45]
	v_pk_mul_f32 v[120:121], v[124:125], v[120:121]
	v_add_f32_e32 v124, 1.0, v183
	v_rcp_f32_e32 v184, v124
	v_add_f32_e32 v124, 1.0, v182
	global_load_dwordx4 v[136:139], v132, s[4:5]
	v_readlane_b32 s4, v255, 29
	v_readlane_b32 s5, v255, 30
	v_rcp_f32_e32 v185, v124
	s_lshl_b32 s13, s96, 3
	v_pk_mul_f32 v[122:123], v[126:127], v[122:123]
	v_mov_b32_e32 v126, 0
	v_pk_mul_f32 v[112:113], v[112:113], v[184:185]
	global_load_dwordx4 v[132:135], v132, s[4:5]
	v_pk_mul_f32 v[116:117], v[116:117], v[112:113]
	v_add_f32_e32 v112, 1.0, v181
	v_add_f32_e32 v113, 1.0, v180
	v_rcp_f32_e32 v112, v112
	v_rcp_f32_e32 v113, v113
	v_readlane_b32 s4, v255, 22
	v_mov_b32_e32 v124, 0
	v_mov_b32_e32 v127, 0
	v_mov_b32_e32 v125, 0
	v_mov_b32_e32 v182, 0
	v_mov_b32_e32 v180, 0
	v_pk_mul_f32 v[112:113], v[114:115], v[112:113]
	v_mov_b32_e32 v183, 0
	v_mov_b32_e32 v181, 0
	s_add_i32 s13, s13, s4
	v_mov_b32_dpp v126, v120 row_shr:1 row_mask:0xf bank_mask:0xf
	v_mov_b32_dpp v124, v120 row_shr:2 row_mask:0xf bank_mask:0xf
	v_mov_b32_dpp v127, v121 row_shr:1 row_mask:0xf bank_mask:0xf
	v_mov_b32_dpp v125, v121 row_shr:2 row_mask:0xf bank_mask:0xf
	v_mov_b32_dpp v182, v122 row_shr:1 row_mask:0xf bank_mask:0xf
	v_mov_b32_dpp v180, v122 row_shr:2 row_mask:0xf bank_mask:0xf
	v_pk_mul_f32 v[114:115], v[118:119], v[112:113]
	v_mov_b32_dpp v183, v123 row_shr:1 row_mask:0xf bank_mask:0xf
	v_mov_b32_dpp v181, v123 row_shr:2 row_mask:0xf bank_mask:0xf
	v_lshlrev_b32_e32 v112, 1, v165
	s_and_saveexec_b64 s[4:5], s[6:7]
	s_cbranch_execz .LBB0_280
	v_or_b32_e32 v118, s13, v149
	v_ashrrev_i32_e32 v119, 31, v118
	v_lshlrev_b64 v[118:119], 11, v[118:119]
	v_lshl_add_u64 v[118:119], s[60:61], 0, v[118:119]
	v_mov_b32_e32 v113, v145
	v_cvt_pk_bf16_f32 v184, v116, v117
	v_cvt_pk_bf16_f32 v185, v114, v115
	v_lshl_add_u64 v[118:119], v[118:119], 0, v[112:113]
	global_store_dwordx2 v[118:119], v[184:185], off

; #define LAS __attribute__((address_space(3)))
; __device__ __forceinline__ unsigned pk_bf16(float lo, float hi) { const f32x2 v = {lo, hi}; return __builtin_bit_cast(unsigned, __builtin_convertvector(v, bf16x2_t)); }
; __device__ __forceinline__ float bf_lo(unsigned u) { return __uint_as_float(u << 16); }
; __device__ __forceinline__ float bf_hi(unsigned u) { return __uint_as_float(u & 0xffff0000u); }
; __device__ __forceinline__ float siluf_(float x) { return x * sigmoidf_(x); }
; template <int PH> ...
;     ...
;     const f32x2 lg = *(const f32x2*)(lng + c2), lb = *(const f32x2*)(lnb + c2);
;     unsigned zz[16];
; #pragma unroll
;     for (int t = 0; t < 16; ++t) zz[t] = __builtin_nontemporal_load((const unsigned*)(SZB + (size_t)(t0 + t) * 1024 + c2));
; #pragma unroll
;     for (int t = 0; t < 16; ++t) {
;         const f32x2 st = *(const LAS f32x2*)(stats + t * 2);
;         const float y0 = (outv[t][0] - st[0]) * st[1] * lg[0] + lb[0], y1 = (outv[t][1] - st[0]) * st[1] * lg[1] + lb[1];
;         __builtin_nontemporal_store(pk_bf16(bf_lo(zz[t]) * siluf_(y0), bf_hi(zz[t]) * siluf_(y1)), (unsigned*)(SZB + (size_t)(t0 + t) * 1024 + c2));
;     }
.Lc31_nostat:
	s_waitcnt lgkmcnt(0)
	s_barrier
	s_waitcnt vmcnt(0)
	s_add_u32 s100, s28, s52
	s_addc_u32 s101, s29, s53
	ds_read_b128 v[228:231], v254 offset:1024
	ds_read_b128 v[232:235], v254 offset:1040
	ds_read_b128 v[236:239], v254 offset:1056
	ds_read_b128 v[240:243], v254 offset:1072
	s_waitcnt lgkmcnt(0)
	v_pk_add_f32 v[154:155], v[154:155], v[228:229] op_sel_hi:[1,0] neg_lo:[0,1] neg_hi:[0,1]
	v_pk_add_f32 v[156:157], v[156:157], v[230:231] op_sel_hi:[1,0] neg_lo:[0,1] neg_hi:[0,1]
	v_pk_mul_f32 v[154:155], v[228:229], v[154:155] op_sel:[1,0]
	v_pk_mul_f32 v[156:157], v[230:231], v[156:157] op_sel:[1,0]
	v_pk_fma_f32 v[154:155], v[154:155], v[220:221], v[222:223]
	v_pk_fma_f32 v[156:157], v[156:157], v[220:221], v[222:223]
	v_pk_mul_f32 v[244:245], v[154:155], s[54:55] op_sel_hi:[1,0]
	v_pk_mul_f32 v[248:249], v[156:157], s[54:55] op_sel_hi:[1,0]
	v_lshlrev_b32_e32 v246, 16, v202
	v_lshlrev_b32_e32 v250, 16, v203
	v_exp_f32_e32 v244, v244
	v_exp_f32_e32 v248, v248
	v_exp_f32_e32 v245, v245
	v_exp_f32_e32 v249, v249
	v_and_b32_e32 v247, 0xffff0000, v202
	v_and_b32_e32 v251, 0xffff0000, v203
	v_add_f32_e32 v244, 1.0, v244
	v_add_f32_e32 v248, 1.0, v248
	v_add_f32_e32 v245, 1.0, v245
	v_add_f32_e32 v249, 1.0, v249
	v_rcp_f32_e32 v244, v244
	v_rcp_f32_e32 v248, v248
	v_rcp_f32_e32 v245, v245
	v_rcp_f32_e32 v249, v249
	v_pk_mul_f32 v[246:247], v[246:247], v[154:155]
	v_pk_mul_f32 v[250:251], v[250:251], v[156:157]
	v_pk_mul_f32 v[246:247], v[246:247], v[244:245]
	v_pk_mul_f32 v[250:251], v[250:251], v[248:249]
	s_nop 0
	v_cvt_pk_bf16_f32 v202, v246, v247
	v_cvt_pk_bf16_f32 v203, v250, v251
	v_pk_add_f32 v[158:159], v[158:159], v[232:233] op_sel_hi:[1,0] neg_lo:[0,1] neg_hi:[0,1]
	v_pk_add_f32 v[160:161], v[160:161], v[234:235] op_sel_hi:[1,0] neg_lo:[0,1] neg_hi:[0,1]
	v_pk_mul_f32 v[158:159], v[232:233], v[158:159] op_sel:[1,0]
	v_pk_mul_f32 v[160:161], v[234:235], v[160:161] op_sel:[1,0]
	v_pk_fma_f32 v[158:159], v[158:159], v[220:221], v[222:223]
	v_pk_fma_f32 v[160:161], v[160:161], v[220:221], v[222:223]
	v_pk_mul_f32 v[244:245], v[158:159], s[54:55] op_sel_hi:[1,0]
	v_pk_mul_f32 v[248:249], v[160:161], s[54:55] op_sel_hi:[1,0]
	v_lshlrev_b32_e32 v246, 16, v204
	v_lshlrev_b32_e32 v250, 16, v205
	v_exp_f32_e32 v244, v244
	v_exp_f32_e32 v248, v248
	v_exp_f32_e32 v245, v245
	v_exp_f32_e32 v249, v249
	v_and_b32_e32 v247, 0xffff0000, v204
	v_and_b32_e32 v251, 0xffff0000, v205
	v_add_f32_e32 v244, 1.0, v244
	v_add_f32_e32 v248, 1.0, v248
	v_add_f32_e32 v245, 1.0, v245
	v_add_f32_e32 v249, 1.0, v249
	v_rcp_f32_e32 v244, v244
	v_rcp_f32_e32 v248, v248
	v_rcp_f32_e32 v245, v245
	v_rcp_f32_e32 v249, v249
	v_pk_mul_f32 v[246:247], v[246:247], v[158:159]
	v_pk_mul_f32 v[250:251], v[250:251], v[160:161]
	v_pk_mul_f32 v[246:247], v[246:247], v[244:245]
	v_pk_mul_f32 v[250:251], v[250:251], v[248:249]
	s_nop 0
	v_cvt_pk_bf16_f32 v204, v246, v247
	v_cvt_pk_bf16_f32 v205, v250, v251
	v_pk_add_f32 v[162:163], v[162:163], v[236:237] op_sel_hi:[1,0] neg_lo:[0,1] neg_hi:[0,1]
	v_pk_add_f32 v[164:165], v[164:165], v[238:239] op_sel_hi:[1,0] neg_lo:[0,1] neg_hi:[0,1]
	v_pk_mul_f32 v[162:163], v[236:237], v[162:163] op_sel:[1,0]
	v_pk_mul_f32 v[164:165], v[238:239], v[164:165] op_sel:[1,0]
	v_pk_fma_f32 v[162:163], v[162:163], v[220:221], v[222:223]
	v_pk_fma_f32 v[164:165], v[164:165], v[220:221], v[222:223]
	v_pk_mul_f32 v[244:245], v[162:163], s[54:55] op_sel_hi:[1,0]
	v_pk_mul_f32 v[248:249], v[164:165], s[54:55] op_sel_hi:[1,0]
	v_lshlrev_b32_e32 v246, 16, v206
	v_lshlrev_b32_e32 v250, 16, v207
	v_exp_f32_e32 v244, v244
	v_exp_f32_e32 v248, v248
	v_exp_f32_e32 v245, v245
	v_exp_f32_e32 v249, v249
	v_and_b32_e32 v247, 0xffff0000, v206
	v_and_b32_e32 v251, 0xffff0000, v207
	v_add_f32_e32 v244, 1.0, v244
	v_add_f32_e32 v248, 1.0, v248
	v_add_f32_e32 v245, 1.0, v245
	v_add_f32_e32 v249, 1.0, v249
	v_rcp_f32_e32 v244, v244
	v_rcp_f32_e32 v248, v248
	v_rcp_f32_e32 v245, v245
	v_rcp_f32_e32 v249, v249
	v_pk_mul_f32 v[246:247], v[246:247], v[162:163]
	v_pk_mul_f32 v[250:251], v[250:251], v[164:165]
	v_pk_mul_f32 v[246:247], v[246:247], v[244:245]
	v_pk_mul_f32 v[250:251], v[250:251], v[248:249]
	s_nop 0
	v_cvt_pk_bf16_f32 v206, v246, v247
	v_cvt_pk_bf16_f32 v207, v250, v251
	v_pk_add_f32 v[166:167], v[166:167], v[240:241] op_sel_hi:[1,0] neg_lo:[0,1] neg_hi:[0,1]
	v_pk_add_f32 v[168:169], v[168:169], v[242:243] op_sel_hi:[1,0] neg_lo:[0,1] neg_hi:[0,1]
	v_pk_mul_f32 v[166:167], v[240:241], v[166:167] op_sel:[1,0]
	v_pk_mul_f32 v[168:169], v[242:243], v[168:169] op_sel:[1,0]
	v_pk_fma_f32 v[166:167], v[166:167], v[220:221], v[222:223]
	v_pk_fma_f32 v[168:169], v[168:169], v[220:221], v[222:223]
	v_pk_mul_f32 v[244:245], v[166:167], s[54:55] op_sel_hi:[1,0]
	v_pk_mul_f32 v[248:249], v[168:169], s[54:55] op_sel_hi:[1,0]
	v_lshlrev_b32_e32 v246, 16, v208
	v_lshlrev_b32_e32 v250, 16, v209
	v_exp_f32_e32 v244, v244
	v_exp_f32_e32 v248, v248
	v_exp_f32_e32 v245, v245
	v_exp_f32_e32 v249, v249
	v_and_b32_e32 v247, 0xffff0000, v208
	v_and_b32_e32 v251, 0xffff0000, v209
	v_add_f32_e32 v244, 1.0, v244
	v_add_f32_e32 v248, 1.0, v248
	v_add_f32_e32 v245, 1.0, v245
	v_add_f32_e32 v249, 1.0, v249
	v_rcp_f32_e32 v244, v244
	v_rcp_f32_e32 v248, v248
	v_rcp_f32_e32 v245, v245
	v_rcp_f32_e32 v249, v249
	v_pk_mul_f32 v[246:247], v[246:247], v[166:167]
	v_pk_mul_f32 v[250:251], v[250:251], v[168:169]
	v_pk_mul_f32 v[246:247], v[246:247], v[244:245]
	v_pk_mul_f32 v[250:251], v[250:251], v[248:249]
	s_nop 0
	v_cvt_pk_bf16_f32 v208, v246, v247
	v_cvt_pk_bf16_f32 v209, v250, v251
	ds_read_b128 v[228:231], v254 offset:1088
	ds_read_b128 v[232:235], v254 offset:1104
	ds_read_b128 v[236:239], v254 offset:1120
	ds_read_b128 v[240:243], v254 offset:1136
	s_waitcnt lgkmcnt(0)
; #define LAS __attribute__((address_space(3)))
; __device__ __forceinline__ unsigned pk_bf16(float lo, float hi) { const f32x2 v = {lo, hi}; return __builtin_bit_cast(unsigned, __builtin_convertvector(v, bf16x2_t)); }
; __device__ __forceinline__ float bf_lo(unsigned u) { return __uint_as_float(u << 16); }
; __device__ __forceinline__ float bf_hi(unsigned u) { return __uint_as_float(u & 0xffff0000u); }
; __device__ __forceinline__ float siluf_(float x) { return x * sigmoidf_(x); }
; template <int PH> ...
;     ...
;     const f32x2 lg = *(const f32x2*)(lng + c2), lb = *(const f32x2*)(lnb + c2);
;     unsigned zz[16];
; #pragma unroll
;     for (int t = 0; t < 16; ++t) zz[t] = __builtin_nontemporal_load((const unsigned*)(SZB + (size_t)(t0 + t) * 1024 + c2));
; #pragma unroll
;     for (int t = 0; t < 16; ++t) {
;         const f32x2 st = *(const LAS f32x2*)(stats + t * 2);
;         const float y0 = (outv[t][0] - st[0]) * st[1] * lg[0] + lb[0], y1 = (outv[t][1] - st[0]) * st[1] * lg[1] + lb[1];
;         __builtin_nontemporal_store(pk_bf16(bf_lo(zz[t]) * siluf_(y0), bf_hi(zz[t]) * siluf_(y1)), (unsigned*)(SZB + (size_t)(t0 + t) * 1024 + c2));
;     }
	v_pk_add_f32 v[170:171], v[170:171], v[228:229] op_sel_hi:[1,0] neg_lo:[0,1] neg_hi:[0,1]
	v_pk_add_f32 v[172:173], v[172:173], v[230:231] op_sel_hi:[1,0] neg_lo:[0,1] neg_hi:[0,1]
	v_pk_mul_f32 v[170:171], v[228:229], v[170:171] op_sel:[1,0]
	v_pk_mul_f32 v[172:173], v[230:231], v[172:173] op_sel:[1,0]
	v_pk_fma_f32 v[170:171], v[170:171], v[220:221], v[222:223]
	v_pk_fma_f32 v[172:173], v[172:173], v[220:221], v[222:223]
	v_pk_mul_f32 v[244:245], v[170:171], s[54:55] op_sel_hi:[1,0]
	v_pk_mul_f32 v[248:249], v[172:173], s[54:55] op_sel_hi:[1,0]
	v_lshlrev_b32_e32 v246, 16, v210
	v_lshlrev_b32_e32 v250, 16, v211
	v_exp_f32_e32 v244, v244
	v_exp_f32_e32 v248, v248
	v_exp_f32_e32 v245, v245
	v_exp_f32_e32 v249, v249
	v_and_b32_e32 v247, 0xffff0000, v210
	v_and_b32_e32 v251, 0xffff0000, v211
	v_add_f32_e32 v244, 1.0, v244
	v_add_f32_e32 v248, 1.0, v248
	v_add_f32_e32 v245, 1.0, v245
	v_add_f32_e32 v249, 1.0, v249
	v_rcp_f32_e32 v244, v244
	v_rcp_f32_e32 v248, v248
	v_rcp_f32_e32 v245, v245
	v_rcp_f32_e32 v249, v249
	v_pk_mul_f32 v[246:247], v[246:247], v[170:171]
	v_pk_mul_f32 v[250:251], v[250:251], v[172:173]
	v_pk_mul_f32 v[246:247], v[246:247], v[244:245]
	v_pk_mul_f32 v[250:251], v[250:251], v[248:249]
	s_nop 0
	v_cvt_pk_bf16_f32 v210, v246, v247
	v_cvt_pk_bf16_f32 v211, v250, v251
	v_pk_add_f32 v[174:175], v[174:175], v[232:233] op_sel_hi:[1,0] neg_lo:[0,1] neg_hi:[0,1]
	v_pk_add_f32 v[176:177], v[176:177], v[234:235] op_sel_hi:[1,0] neg_lo:[0,1] neg_hi:[0,1]
	v_pk_mul_f32 v[174:175], v[232:233], v[174:175] op_sel:[1,0]
	v_pk_mul_f32 v[176:177], v[234:235], v[176:177] op_sel:[1,0]
	v_pk_fma_f32 v[174:175], v[174:175], v[220:221], v[222:223]
	v_pk_fma_f32 v[176:177], v[176:177], v[220:221], v[222:223]
	v_pk_mul_f32 v[244:245], v[174:175], s[54:55] op_sel_hi:[1,0]
	v_pk_mul_f32 v[248:249], v[176:177], s[54:55] op_sel_hi:[1,0]
	v_lshlrev_b32_e32 v246, 16, v212
	v_lshlrev_b32_e32 v250, 16, v213
	v_exp_f32_e32 v244, v244
	v_exp_f32_e32 v248, v248
	v_exp_f32_e32 v245, v245
	v_exp_f32_e32 v249, v249
	v_and_b32_e32 v247, 0xffff0000, v212
	v_and_b32_e32 v251, 0xffff0000, v213
	v_add_f32_e32 v244, 1.0, v244
	v_add_f32_e32 v248, 1.0, v248
	v_add_f32_e32 v245, 1.0, v245
	v_add_f32_e32 v249, 1.0, v249
	v_rcp_f32_e32 v244, v244
	v_rcp_f32_e32 v248, v248
	v_rcp_f32_e32 v245, v245
	v_rcp_f32_e32 v249, v249
	v_pk_mul_f32 v[246:247], v[246:247], v[174:175]
	v_pk_mul_f32 v[250:251], v[250:251], v[176:177]
	v_pk_mul_f32 v[246:247], v[246:247], v[244:245]
	v_pk_mul_f32 v[250:251], v[250:251], v[248:249]
	s_nop 0
	v_cvt_pk_bf16_f32 v212, v246, v247
	v_cvt_pk_bf16_f32 v213, v250, v251
	v_pk_add_f32 v[178:179], v[178:179], v[236:237] op_sel_hi:[1,0] neg_lo:[0,1] neg_hi:[0,1]
	v_pk_add_f32 v[180:181], v[180:181], v[238:239] op_sel_hi:[1,0] neg_lo:[0,1] neg_hi:[0,1]
	v_pk_mul_f32 v[178:179], v[236:237], v[178:179] op_sel:[1,0]
	v_pk_mul_f32 v[180:181], v[238:239], v[180:181] op_sel:[1,0]
	v_pk_fma_f32 v[178:179], v[178:179], v[220:221], v[222:223]
	v_pk_fma_f32 v[180:181], v[180:181], v[220:221], v[222:223]
	v_pk_mul_f32 v[244:245], v[178:179], s[54:55] op_sel_hi:[1,0]
	v_pk_mul_f32 v[248:249], v[180:181], s[54:55] op_sel_hi:[1,0]
	v_lshlrev_b32_e32 v246, 16, v214
	v_lshlrev_b32_e32 v250, 16, v215
	v_exp_f32_e32 v244, v244
	v_exp_f32_e32 v248, v248
	v_exp_f32_e32 v245, v245
	v_exp_f32_e32 v249, v249
	v_and_b32_e32 v247, 0xffff0000, v214
	v_and_b32_e32 v251, 0xffff0000, v215
	v_add_f32_e32 v244, 1.0, v244
	v_add_f32_e32 v248, 1.0, v248
	v_add_f32_e32 v245, 1.0, v245
	v_add_f32_e32 v249, 1.0, v249
	v_rcp_f32_e32 v244, v244
	v_rcp_f32_e32 v248, v248
	v_rcp_f32_e32 v245, v245
	v_rcp_f32_e32 v249, v249
	v_pk_mul_f32 v[246:247], v[246:247], v[178:179]
	v_pk_mul_f32 v[250:251], v[250:251], v[180:181]
	v_pk_mul_f32 v[246:247], v[246:247], v[244:245]
	v_pk_mul_f32 v[250:251], v[250:251], v[248:249]
	s_nop 0
	v_cvt_pk_bf16_f32 v214, v246, v247
	v_cvt_pk_bf16_f32 v215, v250, v251
	v_pk_add_f32 v[182:183], v[182:183], v[240:241] op_sel_hi:[1,0] neg_lo:[0,1] neg_hi:[0,1]
	v_pk_add_f32 v[184:185], v[184:185], v[242:243] op_sel_hi:[1,0] neg_lo:[0,1] neg_hi:[0,1]
	v_pk_mul_f32 v[182:183], v[240:241], v[182:183] op_sel:[1,0]
	v_pk_mul_f32 v[184:185], v[242:243], v[184:185] op_sel:[1,0]
	v_pk_fma_f32 v[182:183], v[182:183], v[220:221], v[222:223]
	v_pk_fma_f32 v[184:185], v[184:185], v[220:221], v[222:223]
	v_pk_mul_f32 v[244:245], v[182:183], s[54:55] op_sel_hi:[1,0]
	v_pk_mul_f32 v[248:249], v[184:185], s[54:55] op_sel_hi:[1,0]
	v_lshlrev_b32_e32 v246, 16, v216
	v_lshlrev_b32_e32 v250, 16, v217
	v_exp_f32_e32 v244, v244
	v_exp_f32_e32 v248, v248
	v_exp_f32_e32 v245, v245
	v_exp_f32_e32 v249, v249
	v_and_b32_e32 v247, 0xffff0000, v216
	v_and_b32_e32 v251, 0xffff0000, v217
	v_add_f32_e32 v244, 1.0, v244
	v_add_f32_e32 v248, 1.0, v248
	v_add_f32_e32 v245, 1.0, v245
	v_add_f32_e32 v249, 1.0, v249
	v_rcp_f32_e32 v244, v244
	v_rcp_f32_e32 v248, v248
	v_rcp_f32_e32 v245, v245
	v_rcp_f32_e32 v249, v249
	v_pk_mul_f32 v[246:247], v[246:247], v[182:183]
	v_pk_mul_f32 v[250:251], v[250:251], v[184:185]
	v_pk_mul_f32 v[246:247], v[246:247], v[244:245]
	v_pk_mul_f32 v[250:251], v[250:251], v[248:249]
	s_nop 0
	v_cvt_pk_bf16_f32 v216, v246, v247
	v_cvt_pk_bf16_f32 v217, v250, v251
	global_store_dword v226, v202, s[100:101] nt
	global_store_dword v226, v203, s[100:101] offset:2048 nt
	s_add_u32 s100, s100, 0x1000
	s_addc_u32 s101, s101, 0
	global_store_dword v226, v204, s[100:101] nt
	global_store_dword v226, v205, s[100:101] offset:2048 nt
	s_add_u32 s100, s100, 0x1000
	s_addc_u32 s101, s101, 0
	global_store_dword v226, v206, s[100:101] nt
	global_store_dword v226, v207, s[100:101] offset:2048 nt
	s_add_u32 s100, s100, 0x1000
	s_addc_u32 s101, s101, 0
	global_store_dword v226, v208, s[100:101] nt
	global_store_dword v226, v209, s[100:101] offset:2048 nt
	s_add_u32 s100, s100, 0x1000
	s_addc_u32 s101, s101, 0
	global_store_dword v226, v210, s[100:101] nt
	global_store_dword v226, v211, s[100:101] offset:2048 nt
	s_add_u32 s100, s100, 0x1000
	s_addc_u32 s101, s101, 0
	global_store_dword v226, v212, s[100:101] nt
	global_store_dword v226, v213, s[100:101] offset:2048 nt
	s_add_u32 s100, s100, 0x1000
	s_addc_u32 s101, s101, 0
	global_store_dword v226, v214, s[100:101] nt
	global_store_dword v226, v215, s[100:101] offset:2048 nt
	s_add_u32 s100, s100, 0x1000
	s_addc_u32 s101, s101, 0
	global_store_dword v226, v216, s[100:101] nt
	global_store_dword v226, v217, s[100:101] offset:2048 nt
	s_cmp_eq_u32 s7, 7
	s_cbranch_scc1 .LBB0_458
; __device__ __forceinline__ void conv31_phase(LAS unsigned char* lds, const bf16_t* GLU, bf16_t* SZB, const float* cw, const float* cb, const float* lng, const float* lnb, int G, int c, const int widx) {
;     ...
;         conv31_chunk<0>(lds, red, stats, GLU, SZB, cw, cb, lng, lnb, T0, true, tid);
;         conv31_chunk<1>(lds, red, stats, GLU, SZB, cw, cb, lng, lnb, T0 + 16, true, tid);
;         conv31_chunk<2>(lds, red, stats, GLU, SZB, cw, cb, lng, lnb, T0 + 32, true, tid);
;         conv31_chunk<3>(lds, red, stats, GLU, SZB, cw, cb, lng, lnb, T0 + 48, true, tid);
;         conv31_chunk<0>(lds, red, stats, GLU, SZB, cw, cb, lng, lnb, T0 + 64, true, tid);
;         conv31_chunk<1>(lds, red, stats, GLU, SZB, cw, cb, lng, lnb, T0 + 80, true, tid);
;         conv31_chunk<2>(lds, red, stats, GLU, SZB, cw, cb, lng, lnb, T0 + 96, true, tid);
;         conv31_chunk<3>(lds, red, stats, GLU, SZB, cw, cb, lng, lnb, T0 + 112, false, tid);
	v_mov_b64_e32 v[0:1], v[32:33]
	v_mov_b64_e32 v[2:3], v[34:35]
	v_mov_b64_e32 v[4:5], v[36:37]
	v_mov_b64_e32 v[6:7], v[38:39]
	v_mov_b64_e32 v[8:9], v[40:41]
	v_mov_b64_e32 v[10:11], v[42:43]
	v_mov_b64_e32 v[12:13], v[44:45]
	v_mov_b64_e32 v[14:15], v[46:47]
	v_mov_b64_e32 v[16:17], v[48:49]
	v_mov_b64_e32 v[18:19], v[50:51]
	v_mov_b64_e32 v[20:21], v[52:53]
	v_mov_b64_e32 v[22:23], v[54:55]
	v_mov_b64_e32 v[24:25], v[56:57]
	v_mov_b64_e32 v[26:27], v[58:59]
	v_mov_b64_e32 v[28:29], v[60:61]
	v_mov_b64_e32 v[30:31], v[62:63]
	v_mov_b64_e32 v[32:33], v[64:65]
	v_mov_b64_e32 v[34:35], v[66:67]
	v_mov_b64_e32 v[36:37], v[68:69]
	v_mov_b64_e32 v[38:39], v[70:71]
	v_mov_b64_e32 v[40:41], v[72:73]
	v_mov_b64_e32 v[42:43], v[74:75]
	v_mov_b64_e32 v[44:45], v[76:77]
	v_mov_b64_e32 v[46:47], v[78:79]
	v_mov_b64_e32 v[48:49], v[80:81]
	v_mov_b64_e32 v[50:51], v[82:83]
	v_mov_b64_e32 v[52:53], v[84:85]
	v_mov_b64_e32 v[54:55], v[86:87]
	v_mov_b64_e32 v[56:57], v[88:89]
	v_mov_b64_e32 v[58:59], v[90:91]
	v_and_b32_e32 v61, 0xffff0000, v186
	v_lshlrev_b32_e32 v60, 16, v186
	v_and_b32_e32 v63, 0xffff0000, v187
	v_lshlrev_b32_e32 v62, 16, v187
	v_and_b32_e32 v65, 0xffff0000, v188
	v_lshlrev_b32_e32 v64, 16, v188
	v_and_b32_e32 v67, 0xffff0000, v189
	v_lshlrev_b32_e32 v66, 16, v189
	v_and_b32_e32 v69, 0xffff0000, v190
	v_lshlrev_b32_e32 v68, 16, v190
	v_and_b32_e32 v71, 0xffff0000, v191
	v_lshlrev_b32_e32 v70, 16, v191
	v_and_b32_e32 v73, 0xffff0000, v192
	v_lshlrev_b32_e32 v72, 16, v192
	v_and_b32_e32 v75, 0xffff0000, v193
	v_lshlrev_b32_e32 v74, 16, v193
	v_and_b32_e32 v77, 0xffff0000, v194
	v_lshlrev_b32_e32 v76, 16, v194
	v_and_b32_e32 v79, 0xffff0000, v195
	v_lshlrev_b32_e32 v78, 16, v195
	v_and_b32_e32 v81, 0xffff0000, v196
	v_lshlrev_b32_e32 v80, 16, v196
	v_and_b32_e32 v83, 0xffff0000, v197
	v_lshlrev_b32_e32 v82, 16, v197
	v_and_b32_e32 v85, 0xffff0000, v198
	v_lshlrev_b32_e32 v84, 16, v198
	v_and_b32_e32 v87, 0xffff0000, v199
	v_lshlrev_b32_e32 v86, 16, v199
	v_and_b32_e32 v89, 0xffff0000, v200
	v_lshlrev_b32_e32 v88, 16, v200
	v_and_b32_e32 v91, 0xffff0000, v201
	v_lshlrev_b32_e32 v90, 16, v201
	s_add_i32 s7, s7, 1
	s_add_i32 s34, s34, 16
	s_branch .Lc31_chunk
